# GEMM: accumulator zeroing moved from the unit preamble into the first load segment of the K-loop (first iteration only), overlapping LDS/DMA latency
# baseline (speedup 1.0000x reference)
.LBB0_252:
	s_ashr_i32 s19, s18, 31
	s_lshl_b64 s[0:1], s[18:19], 19
	s_add_u32 s20, s33, s0
	s_addc_u32 s21, s34, s1
	s_and_b64 s[0:1], s[4:5], exec
	s_cselect_b32 s19, s21, s31
	s_cselect_b32 s50, s20, s30
	s_ashr_i32 s11, s10, 31
	s_lshl_b64 s[0:1], s[10:11], 19
	s_add_u32 s22, s35, s0
	s_addc_u32 s23, s36, s1
	s_and_b64 s[0:1], s[4:5], exec
	s_cselect_b32 s11, s23, s27
	s_cselect_b32 s51, s22, s26
	s_add_u32 s0, s30, 0x40080
	s_addc_u32 s1, s31, 0
	s_add_u32 s52, s26, 0x100
	s_addc_u32 s53, s27, 0
	s_mov_b32 s54, -2
	.p2alignl 6, 3212836864
.LBB0_253:
	s_add_u32 s26, s0, 0xfffc0080
	s_addc_u32 s27, s1, -1
	s_add_i32 s55, 0, 0x10000
	s_cmp_eq_u32 s54, 12
	s_cselect_b32 s31, s19, s27
	s_cselect_b32 s30, s50, s26
	v_add_u32_e32 v138, s55, v141
	s_cselect_b32 s27, s11, s53
	s_cselect_b32 s26, s51, s52
	s_add_i32 s58, 0, 0x14000
	ds_read_b128 v[144:147], v138
	ds_read_b128 v[158:161], v138 offset:1024
	ds_read_b128 v[162:165], v138 offset:2048
	ds_read_b128 v[166:169], v138 offset:3072
	v_add_u32_e32 v138, s58, v141
	ds_read_b128 v[170:173], v138
	ds_read_b128 v[174:177], v138 offset:1024
	ds_read_b128 v[178:181], v138 offset:2048
	ds_read_b128 v[182:185], v138 offset:3072
	v_lshl_add_u64 v[138:139], s[0:1], 0, v[134:135]
	s_add_i32 m0, s38, 0xc000
	ds_read_b128 v[186:189], v143
	ds_read_b128 v[190:193], v143 offset:1024
	ds_read_b128 v[194:197], v143 offset:2048
	ds_read_b128 v[198:201], v143 offset:3072
	ds_read_b128 v[202:205], v143 offset:4096
	ds_read_b128 v[218:221], v143 offset:5120
	ds_read_b128 v[222:225], v143 offset:6144
	ds_read_b128 v[226:229], v143 offset:7168
	global_load_lds_dwordx4 v[138:139], off
	v_lshl_add_u64 v[138:139], s[0:1], 0, v[136:137]
	s_add_i32 m0, s38, 0xe000
	s_nop 0
	global_load_lds_dwordx4 v[138:139], off
	s_cmp_lg_u32 s54, -2
	s_cbranch_scc1 .Lz_skip_0
	v_mov_b64_e32 v[0:1], 0
	v_mov_b64_e32 v[2:3], 0
	v_mov_b64_e32 v[8:9], 0
	v_mov_b64_e32 v[10:11], 0
	v_mov_b64_e32 v[16:17], 0
	v_mov_b64_e32 v[18:19], 0
	v_mov_b64_e32 v[24:25], 0
	v_mov_b64_e32 v[26:27], 0
	v_mov_b64_e32 v[32:33], 0
	v_mov_b64_e32 v[34:35], 0
	v_mov_b64_e32 v[40:41], 0
	v_mov_b64_e32 v[42:43], 0
	v_mov_b64_e32 v[48:49], 0
	v_mov_b64_e32 v[50:51], 0
	v_mov_b64_e32 v[56:57], 0
	v_mov_b64_e32 v[58:59], 0
	v_mov_b64_e32 v[4:5], 0
	v_mov_b64_e32 v[6:7], 0
	v_mov_b64_e32 v[12:13], 0
	v_mov_b64_e32 v[14:15], 0
	v_mov_b64_e32 v[20:21], 0
	v_mov_b64_e32 v[22:23], 0
	v_mov_b64_e32 v[28:29], 0
	v_mov_b64_e32 v[30:31], 0
	v_mov_b64_e32 v[36:37], 0
	v_mov_b64_e32 v[38:39], 0
	v_mov_b64_e32 v[44:45], 0
	v_mov_b64_e32 v[46:47], 0
	v_mov_b64_e32 v[52:53], 0
	v_mov_b64_e32 v[54:55], 0
	v_mov_b64_e32 v[60:61], 0
	v_mov_b64_e32 v[62:63], 0
	v_mov_b64_e32 v[64:65], 0
	v_mov_b64_e32 v[66:67], 0
	v_mov_b64_e32 v[72:73], 0
	v_mov_b64_e32 v[74:75], 0
	v_mov_b64_e32 v[80:81], 0
	v_mov_b64_e32 v[82:83], 0
	v_mov_b64_e32 v[88:89], 0
	v_mov_b64_e32 v[90:91], 0
	v_mov_b64_e32 v[96:97], 0
	v_mov_b64_e32 v[98:99], 0
	v_mov_b64_e32 v[104:105], 0
	v_mov_b64_e32 v[106:107], 0
	v_mov_b64_e32 v[112:113], 0
	v_mov_b64_e32 v[114:115], 0
	v_mov_b64_e32 v[120:121], 0
	v_mov_b64_e32 v[122:123], 0
	v_mov_b64_e32 v[68:69], 0
	v_mov_b64_e32 v[70:71], 0
	v_mov_b64_e32 v[76:77], 0
	v_mov_b64_e32 v[78:79], 0
	v_mov_b64_e32 v[84:85], 0
	v_mov_b64_e32 v[86:87], 0
	v_mov_b64_e32 v[92:93], 0
	v_mov_b64_e32 v[94:95], 0
	v_mov_b64_e32 v[100:101], 0
	v_mov_b64_e32 v[102:103], 0
	v_mov_b64_e32 v[108:109], 0
	v_mov_b64_e32 v[110:111], 0
	v_mov_b64_e32 v[116:117], 0
	v_mov_b64_e32 v[118:119], 0
	v_mov_b64_e32 v[124:125], 0
	v_mov_b64_e32 v[126:127], 0
.Lz_skip_0:
	s_waitcnt vmcnt(8)
	s_waitcnt lgkmcnt(0)
	s_barrier
	s_waitcnt lgkmcnt(0)
	v_mfma_f32_16x16x32_bf16 v[124:127], v[144:147], v[186:189], v[124:127]
	v_mfma_f32_16x16x32_bf16 v[116:119], v[162:165], v[186:189], v[116:119]
	v_mfma_f32_16x16x32_bf16 v[108:111], v[144:147], v[194:197], v[108:111]
	v_mfma_f32_16x16x32_bf16 v[100:103], v[162:165], v[194:197], v[100:103]
	v_mfma_f32_16x16x32_bf16 v[92:95], v[144:147], v[202:205], v[92:95]
	v_mfma_f32_16x16x32_bf16 v[84:87], v[162:165], v[202:205], v[84:87]
	v_mfma_f32_16x16x32_bf16 v[76:79], v[144:147], v[222:225], v[76:79]
	v_mfma_f32_16x16x32_bf16 v[68:71], v[162:165], v[222:225], v[68:71]
	v_mfma_f32_16x16x32_bf16 v[124:127], v[158:161], v[190:193], v[124:127]
	v_mfma_f32_16x16x32_bf16 v[116:119], v[166:169], v[190:193], v[116:119]
	v_mfma_f32_16x16x32_bf16 v[108:111], v[158:161], v[198:201], v[108:111]
	v_mfma_f32_16x16x32_bf16 v[100:103], v[166:169], v[198:201], v[100:103]
	v_mfma_f32_16x16x32_bf16 v[92:95], v[158:161], v[218:221], v[92:95]
	v_mfma_f32_16x16x32_bf16 v[84:87], v[166:169], v[218:221], v[84:87]
	v_mfma_f32_16x16x32_bf16 v[76:79], v[158:161], v[226:229], v[76:79]
	v_mfma_f32_16x16x32_bf16 v[68:71], v[166:169], v[226:229], v[68:71]
	v_mfma_f32_16x16x32_bf16 v[120:123], v[170:173], v[186:189], v[120:123]
	v_mfma_f32_16x16x32_bf16 v[112:115], v[178:181], v[186:189], v[112:115]
	v_mfma_f32_16x16x32_bf16 v[104:107], v[170:173], v[194:197], v[104:107]
	v_mfma_f32_16x16x32_bf16 v[96:99], v[178:181], v[194:197], v[96:99]
	v_mfma_f32_16x16x32_bf16 v[88:91], v[170:173], v[202:205], v[88:91]
	v_mfma_f32_16x16x32_bf16 v[80:83], v[178:181], v[202:205], v[80:83]
	v_mfma_f32_16x16x32_bf16 v[72:75], v[170:173], v[222:225], v[72:75]
	v_mfma_f32_16x16x32_bf16 v[64:67], v[178:181], v[222:225], v[64:67]
	v_mfma_f32_16x16x32_bf16 v[120:123], v[174:177], v[190:193], v[120:123]
	v_mfma_f32_16x16x32_bf16 v[112:115], v[182:185], v[190:193], v[112:115]
	v_mfma_f32_16x16x32_bf16 v[104:107], v[174:177], v[198:201], v[104:107]
	v_mfma_f32_16x16x32_bf16 v[96:99], v[182:185], v[198:201], v[96:99]
	v_mfma_f32_16x16x32_bf16 v[88:91], v[174:177], v[218:221], v[88:91]
	v_mfma_f32_16x16x32_bf16 v[80:83], v[182:185], v[218:221], v[80:83]
	v_mfma_f32_16x16x32_bf16 v[72:75], v[174:177], v[226:229], v[72:75]
	v_mfma_f32_16x16x32_bf16 v[64:67], v[182:185], v[226:229], v[64:67]
	s_barrier
	s_add_i32 s55, s55, s37
	v_lshl_add_u64 v[138:139], s[26:27], 0, v[148:149]
	s_mov_b32 m0, s55
	ds_read_b128 v[186:189], v143 offset:16384
	ds_read_b128 v[190:193], v143 offset:17408
	ds_read_b128 v[194:197], v143 offset:18432
	ds_read_b128 v[198:201], v143 offset:19456
	ds_read_b128 v[202:205], v143 offset:20480
	ds_read_b128 v[218:221], v143 offset:21504
	ds_read_b128 v[222:225], v143 offset:22528
	ds_read_b128 v[226:229], v143 offset:23552
	global_load_lds_dwordx4 v[138:139], off
	s_add_i32 m0, s55, 0x2000
	s_add_u32 s56, s26, 0x40000
	v_lshl_add_u64 v[154:155], s[26:27], 0, v[128:129]
	s_addc_u32 s57, s27, 0
	s_add_i32 s55, s58, s37
	global_load_lds_dwordx4 v[154:155], off
	v_lshl_add_u64 v[156:157], s[56:57], 0, v[148:149]
	s_mov_b32 m0, s55
	v_lshl_add_u64 v[212:213], s[30:31], 0, v[130:131]
	global_load_lds_dwordx4 v[156:157], off
	v_lshl_add_u64 v[156:157], s[56:57], 0, v[128:129]
	s_add_i32 m0, s55, 0x2000
	s_nop 0
	global_load_lds_dwordx4 v[156:157], off
	v_lshl_add_u64 v[156:157], s[30:31], 0, v[132:133]
	s_mov_b32 m0, s38
	s_nop 0
	global_load_lds_dwordx4 v[156:157], off
	s_mov_b32 m0, s39
	s_nop 0
	global_load_lds_dwordx4 v[212:213], off
	s_waitcnt vmcnt(8)
	s_waitcnt lgkmcnt(0)
	s_barrier
	s_waitcnt lgkmcnt(0)
	v_mfma_f32_16x16x32_bf16 v[60:63], v[144:147], v[186:189], v[60:63]
	v_mfma_f32_16x16x32_bf16 v[52:55], v[162:165], v[186:189], v[52:55]
	v_mfma_f32_16x16x32_bf16 v[44:47], v[144:147], v[194:197], v[44:47]
	v_mfma_f32_16x16x32_bf16 v[36:39], v[162:165], v[194:197], v[36:39]
	v_mfma_f32_16x16x32_bf16 v[28:31], v[144:147], v[202:205], v[28:31]
	v_mfma_f32_16x16x32_bf16 v[20:23], v[162:165], v[202:205], v[20:23]
	v_mfma_f32_16x16x32_bf16 v[12:15], v[144:147], v[222:225], v[12:15]
	v_mfma_f32_16x16x32_bf16 v[4:7], v[162:165], v[222:225], v[4:7]
	v_mfma_f32_16x16x32_bf16 v[60:63], v[158:161], v[190:193], v[60:63]
	v_mfma_f32_16x16x32_bf16 v[52:55], v[166:169], v[190:193], v[52:55]
	v_mfma_f32_16x16x32_bf16 v[44:47], v[158:161], v[198:201], v[44:47]
	v_mfma_f32_16x16x32_bf16 v[36:39], v[166:169], v[198:201], v[36:39]
	v_mfma_f32_16x16x32_bf16 v[28:31], v[158:161], v[218:221], v[28:31]
	v_mfma_f32_16x16x32_bf16 v[20:23], v[166:169], v[218:221], v[20:23]
	v_mfma_f32_16x16x32_bf16 v[12:15], v[158:161], v[226:229], v[12:15]
	v_mfma_f32_16x16x32_bf16 v[4:7], v[166:169], v[226:229], v[4:7]
	v_mfma_f32_16x16x32_bf16 v[56:59], v[170:173], v[186:189], v[56:59]
	v_mfma_f32_16x16x32_bf16 v[48:51], v[178:181], v[186:189], v[48:51]
	v_mfma_f32_16x16x32_bf16 v[40:43], v[170:173], v[194:197], v[40:43]
	v_mfma_f32_16x16x32_bf16 v[32:35], v[178:181], v[194:197], v[32:35]
	v_mfma_f32_16x16x32_bf16 v[24:27], v[170:173], v[202:205], v[24:27]
	v_mfma_f32_16x16x32_bf16 v[16:19], v[178:181], v[202:205], v[16:19]
	v_mfma_f32_16x16x32_bf16 v[8:11], v[170:173], v[222:225], v[8:11]
	v_mfma_f32_16x16x32_bf16 v[0:3], v[178:181], v[222:225], v[0:3]
	v_mfma_f32_16x16x32_bf16 v[56:59], v[174:177], v[190:193], v[56:59]
	v_mfma_f32_16x16x32_bf16 v[48:51], v[182:185], v[190:193], v[48:51]
	v_mfma_f32_16x16x32_bf16 v[40:43], v[174:177], v[198:201], v[40:43]
	v_mfma_f32_16x16x32_bf16 v[32:35], v[182:185], v[198:201], v[32:35]
	v_mfma_f32_16x16x32_bf16 v[24:27], v[174:177], v[218:221], v[24:27]
	v_mfma_f32_16x16x32_bf16 v[16:19], v[182:185], v[218:221], v[16:19]
	v_mfma_f32_16x16x32_bf16 v[8:11], v[174:177], v[226:229], v[8:11]
	v_mfma_f32_16x16x32_bf16 v[0:3], v[182:185], v[226:229], v[0:3]
	s_barrier
	s_add_i32 s55, 0, 0x18000
	v_add_u32_e32 v140, s55, v141
	s_add_i32 s56, 0, 0x1c000
	ds_read_b128 v[144:147], v140
	ds_read_b128 v[158:161], v140 offset:1024
	ds_read_b128 v[162:165], v140 offset:2048
	ds_read_b128 v[166:169], v140 offset:3072
	v_add_u32_e32 v140, s56, v141
	ds_read_b128 v[170:173], v140
	ds_read_b128 v[174:177], v140 offset:1024
	ds_read_b128 v[178:181], v140 offset:2048
	ds_read_b128 v[182:185], v140 offset:3072
	s_add_u32 s30, s30, 0x40000
	s_addc_u32 s31, s31, 0
	s_mov_b32 m0, s40
	v_lshl_add_u64 v[214:215], s[30:31], 0, v[132:133]
	ds_read_b128 v[186:189], v143 offset:32768
	ds_read_b128 v[190:193], v143 offset:33792
	ds_read_b128 v[194:197], v143 offset:34816
	ds_read_b128 v[198:201], v143 offset:35840
	ds_read_b128 v[202:205], v143 offset:36864
	ds_read_b128 v[218:221], v143 offset:37888
	ds_read_b128 v[222:225], v143 offset:38912
	ds_read_b128 v[226:229], v143 offset:39936
	global_load_lds_dwordx4 v[214:215], off
	v_lshl_add_u64 v[214:215], s[30:31], 0, v[130:131]
	s_mov_b32 m0, s41
	s_nop 0
	global_load_lds_dwordx4 v[214:215], off
	s_waitcnt vmcnt(8)
	s_waitcnt lgkmcnt(0)
	s_barrier
	s_waitcnt lgkmcnt(0)
	v_mfma_f32_16x16x32_bf16 v[124:127], v[144:147], v[186:189], v[124:127]
	v_mfma_f32_16x16x32_bf16 v[116:119], v[162:165], v[186:189], v[116:119]
	v_mfma_f32_16x16x32_bf16 v[108:111], v[144:147], v[194:197], v[108:111]
	v_mfma_f32_16x16x32_bf16 v[100:103], v[162:165], v[194:197], v[100:103]
	v_mfma_f32_16x16x32_bf16 v[92:95], v[144:147], v[202:205], v[92:95]
	v_mfma_f32_16x16x32_bf16 v[84:87], v[162:165], v[202:205], v[84:87]
	v_mfma_f32_16x16x32_bf16 v[76:79], v[144:147], v[222:225], v[76:79]
	v_mfma_f32_16x16x32_bf16 v[68:71], v[162:165], v[222:225], v[68:71]
	v_mfma_f32_16x16x32_bf16 v[124:127], v[158:161], v[190:193], v[124:127]
	v_mfma_f32_16x16x32_bf16 v[116:119], v[166:169], v[190:193], v[116:119]
	v_mfma_f32_16x16x32_bf16 v[108:111], v[158:161], v[198:201], v[108:111]
	v_mfma_f32_16x16x32_bf16 v[100:103], v[166:169], v[198:201], v[100:103]
	v_mfma_f32_16x16x32_bf16 v[92:95], v[158:161], v[218:221], v[92:95]
	v_mfma_f32_16x16x32_bf16 v[84:87], v[166:169], v[218:221], v[84:87]
	v_mfma_f32_16x16x32_bf16 v[76:79], v[158:161], v[226:229], v[76:79]
	v_mfma_f32_16x16x32_bf16 v[68:71], v[166:169], v[226:229], v[68:71]
	v_mfma_f32_16x16x32_bf16 v[120:123], v[170:173], v[186:189], v[120:123]
	v_mfma_f32_16x16x32_bf16 v[112:115], v[178:181], v[186:189], v[112:115]
	v_mfma_f32_16x16x32_bf16 v[104:107], v[170:173], v[194:197], v[104:107]
	v_mfma_f32_16x16x32_bf16 v[96:99], v[178:181], v[194:197], v[96:99]
	v_mfma_f32_16x16x32_bf16 v[88:91], v[170:173], v[202:205], v[88:91]
	v_mfma_f32_16x16x32_bf16 v[80:83], v[178:181], v[202:205], v[80:83]
	v_mfma_f32_16x16x32_bf16 v[72:75], v[170:173], v[222:225], v[72:75]
	v_mfma_f32_16x16x32_bf16 v[64:67], v[178:181], v[222:225], v[64:67]
	v_mfma_f32_16x16x32_bf16 v[120:123], v[174:177], v[190:193], v[120:123]
	v_mfma_f32_16x16x32_bf16 v[112:115], v[182:185], v[190:193], v[112:115]
	v_mfma_f32_16x16x32_bf16 v[104:107], v[174:177], v[198:201], v[104:107]
	v_mfma_f32_16x16x32_bf16 v[96:99], v[182:185], v[198:201], v[96:99]
	v_mfma_f32_16x16x32_bf16 v[88:91], v[174:177], v[218:221], v[88:91]
	v_mfma_f32_16x16x32_bf16 v[80:83], v[182:185], v[218:221], v[80:83]
	v_mfma_f32_16x16x32_bf16 v[72:75], v[174:177], v[226:229], v[72:75]
	v_mfma_f32_16x16x32_bf16 v[64:67], v[182:185], v[226:229], v[64:67]
	s_barrier
	s_add_i32 s30, s55, s37
	v_lshl_add_u64 v[138:139], v[138:139], 0, s[28:29]
	s_mov_b32 m0, s30
	ds_read_b128 v[186:189], v143 offset:49152
	ds_read_b128 v[190:193], v143 offset:50176
	ds_read_b128 v[194:197], v143 offset:51200
	ds_read_b128 v[198:201], v143 offset:52224
	ds_read_b128 v[202:205], v143 offset:53248
	ds_read_b128 v[218:221], v143 offset:54272
	ds_read_b128 v[222:225], v143 offset:55296
	ds_read_b128 v[226:229], v143 offset:56320
	global_load_lds_dwordx4 v[138:139], off
	s_add_i32 m0, s30, 0x2000
	s_add_u32 s26, s26, 0x40080
	v_lshl_add_u64 v[138:139], v[154:155], 0, s[28:29]
	s_addc_u32 s27, s27, 0
	s_add_i32 s30, s56, s37
	global_load_lds_dwordx4 v[138:139], off
	v_lshl_add_u64 v[138:139], s[26:27], 0, v[148:149]
	s_mov_b32 m0, s30
	s_nop 0
	global_load_lds_dwordx4 v[138:139], off
	v_lshl_add_u64 v[138:139], s[26:27], 0, v[128:129]
	s_add_i32 m0, s30, 0x2000
	s_nop 0
	global_load_lds_dwordx4 v[138:139], off
	v_lshl_add_u64 v[138:139], v[156:157], 0, s[28:29]
	s_mov_b32 m0, s46
	s_nop 0
	global_load_lds_dwordx4 v[138:139], off
	v_lshl_add_u64 v[138:139], v[212:213], 0, s[28:29]
	s_mov_b32 m0, s47
	s_nop 0
	global_load_lds_dwordx4 v[138:139], off
	s_waitcnt vmcnt(8)
	s_waitcnt lgkmcnt(0)
	s_barrier
	s_waitcnt lgkmcnt(0)
	v_mfma_f32_16x16x32_bf16 v[60:63], v[144:147], v[186:189], v[60:63]
	v_mfma_f32_16x16x32_bf16 v[52:55], v[162:165], v[186:189], v[52:55]
	v_mfma_f32_16x16x32_bf16 v[44:47], v[144:147], v[194:197], v[44:47]
	v_mfma_f32_16x16x32_bf16 v[36:39], v[162:165], v[194:197], v[36:39]
	v_mfma_f32_16x16x32_bf16 v[28:31], v[144:147], v[202:205], v[28:31]
	v_mfma_f32_16x16x32_bf16 v[20:23], v[162:165], v[202:205], v[20:23]
	v_mfma_f32_16x16x32_bf16 v[12:15], v[144:147], v[222:225], v[12:15]
	v_mfma_f32_16x16x32_bf16 v[4:7], v[162:165], v[222:225], v[4:7]
	v_mfma_f32_16x16x32_bf16 v[60:63], v[158:161], v[190:193], v[60:63]
	v_mfma_f32_16x16x32_bf16 v[52:55], v[166:169], v[190:193], v[52:55]
	v_mfma_f32_16x16x32_bf16 v[44:47], v[158:161], v[198:201], v[44:47]
	v_mfma_f32_16x16x32_bf16 v[36:39], v[166:169], v[198:201], v[36:39]
	v_mfma_f32_16x16x32_bf16 v[28:31], v[158:161], v[218:221], v[28:31]
	v_mfma_f32_16x16x32_bf16 v[20:23], v[166:169], v[218:221], v[20:23]
	v_mfma_f32_16x16x32_bf16 v[12:15], v[158:161], v[226:229], v[12:15]
	v_mfma_f32_16x16x32_bf16 v[4:7], v[166:169], v[226:229], v[4:7]
	v_mfma_f32_16x16x32_bf16 v[56:59], v[170:173], v[186:189], v[56:59]
	v_mfma_f32_16x16x32_bf16 v[48:51], v[178:181], v[186:189], v[48:51]
	v_mfma_f32_16x16x32_bf16 v[40:43], v[170:173], v[194:197], v[40:43]
	v_mfma_f32_16x16x32_bf16 v[32:35], v[178:181], v[194:197], v[32:35]
	v_mfma_f32_16x16x32_bf16 v[24:27], v[170:173], v[202:205], v[24:27]
	v_mfma_f32_16x16x32_bf16 v[16:19], v[178:181], v[202:205], v[16:19]
	v_mfma_f32_16x16x32_bf16 v[8:11], v[170:173], v[222:225], v[8:11]
	v_mfma_f32_16x16x32_bf16 v[0:3], v[178:181], v[222:225], v[0:3]
	v_mfma_f32_16x16x32_bf16 v[56:59], v[174:177], v[190:193], v[56:59]
	v_mfma_f32_16x16x32_bf16 v[48:51], v[182:185], v[190:193], v[48:51]
	v_mfma_f32_16x16x32_bf16 v[40:43], v[174:177], v[198:201], v[40:43]
	v_mfma_f32_16x16x32_bf16 v[32:35], v[182:185], v[198:201], v[32:35]
	v_mfma_f32_16x16x32_bf16 v[24:27], v[174:177], v[218:221], v[24:27]
	v_mfma_f32_16x16x32_bf16 v[16:19], v[182:185], v[218:221], v[16:19]
	v_mfma_f32_16x16x32_bf16 v[8:11], v[174:177], v[226:229], v[8:11]
	v_mfma_f32_16x16x32_bf16 v[0:3], v[182:185], v[226:229], v[0:3]
	s_barrier
	s_add_i32 s54, s54, 2
	s_add_u32 s0, s0, 0x100
	s_addc_u32 s1, s1, 0
	s_add_u32 s52, s52, 0x100
	s_addc_u32 s53, s53, 0
	s_cmp_gt_u32 s54, 13
	s_cbranch_scc0 .LBB0_253
	s_and_b64 vcc, exec, s[8:9]
	s_cbranch_vccz .LBB0_256
	s_barrier

.LBB0_359:
	s_add_u32 s42, s8, 0x100
	s_addc_u32 s43, s9, 0
	s_mov_b32 s44, -2
	.p2alignl 6, 3212836864
.LBB0_360:
	s_add_u32 s0, s4, 0x100
	s_addc_u32 s1, s5, 0
	s_add_i32 s45, 0, 0x10000
	s_cmp_eq_u32 s44, 40
	s_cselect_b32 s9, s39, s1
	s_cselect_b32 s8, s38, s0
	v_add_u32_e32 v146, s45, v168
	s_cselect_b32 s3, s41, s43
	s_cselect_b32 s2, s40, s42
	s_add_i32 s62, 0, 0x14000
	ds_read_b128 v[128:131], v146
	ds_read_b128 v[132:135], v146 offset:1024
	ds_read_b128 v[158:161], v146 offset:2048
	ds_read_b128 v[162:165], v146 offset:3072
	v_add_u32_e32 v146, s62, v168
	ds_read_b128 v[170:173], v146
	ds_read_b128 v[174:177], v146 offset:1024
	ds_read_b128 v[178:181], v146 offset:2048
	ds_read_b128 v[182:185], v146 offset:3072
	v_lshl_add_u64 v[146:147], s[4:5], 0, v[142:143]
	s_add_i32 m0, s50, 0xc000
	ds_read_b128 v[186:189], v169
	ds_read_b128 v[190:193], v169 offset:1024
	ds_read_b128 v[194:197], v169 offset:2048
	ds_read_b128 v[198:201], v169 offset:3072
	ds_read_b128 v[202:205], v169 offset:4096
	ds_read_b128 v[218:221], v169 offset:5120
	ds_read_b128 v[222:225], v169 offset:6144
	ds_read_b128 v[226:229], v169 offset:7168
	global_load_lds_dwordx4 v[146:147], off
	v_lshl_add_u64 v[146:147], s[4:5], 0, v[144:145]
	s_add_i32 m0, s50, 0xe000
	s_nop 0
	global_load_lds_dwordx4 v[146:147], off
	s_cmp_lg_u32 s44, -2
	s_cbranch_scc1 .Lz_skip_1
	v_mov_b64_e32 v[0:1], 0
	v_mov_b64_e32 v[2:3], 0
	v_mov_b64_e32 v[4:5], 0
	v_mov_b64_e32 v[6:7], 0
	v_mov_b64_e32 v[16:17], 0
	v_mov_b64_e32 v[18:19], 0
	v_mov_b64_e32 v[20:21], 0
	v_mov_b64_e32 v[22:23], 0
	v_mov_b64_e32 v[32:33], 0
	v_mov_b64_e32 v[34:35], 0
	v_mov_b64_e32 v[36:37], 0
	v_mov_b64_e32 v[38:39], 0
	v_mov_b64_e32 v[48:49], 0
	v_mov_b64_e32 v[50:51], 0
	v_mov_b64_e32 v[52:53], 0
	v_mov_b64_e32 v[54:55], 0
	v_mov_b64_e32 v[8:9], 0
	v_mov_b64_e32 v[10:11], 0
	v_mov_b64_e32 v[12:13], 0
	v_mov_b64_e32 v[14:15], 0
	v_mov_b64_e32 v[24:25], 0
	v_mov_b64_e32 v[26:27], 0
	v_mov_b64_e32 v[28:29], 0
	v_mov_b64_e32 v[30:31], 0
	v_mov_b64_e32 v[40:41], 0
	v_mov_b64_e32 v[42:43], 0
	v_mov_b64_e32 v[44:45], 0
	v_mov_b64_e32 v[46:47], 0
	v_mov_b64_e32 v[56:57], 0
	v_mov_b64_e32 v[58:59], 0
	v_mov_b64_e32 v[60:61], 0
	v_mov_b64_e32 v[62:63], 0
	v_mov_b64_e32 v[64:65], 0
	v_mov_b64_e32 v[66:67], 0
	v_mov_b64_e32 v[68:69], 0
	v_mov_b64_e32 v[70:71], 0
	v_mov_b64_e32 v[80:81], 0
	v_mov_b64_e32 v[82:83], 0
	v_mov_b64_e32 v[84:85], 0
	v_mov_b64_e32 v[86:87], 0
	v_mov_b64_e32 v[96:97], 0
	v_mov_b64_e32 v[98:99], 0
	v_mov_b64_e32 v[100:101], 0
	v_mov_b64_e32 v[102:103], 0
	v_mov_b64_e32 v[112:113], 0
	v_mov_b64_e32 v[114:115], 0
	v_mov_b64_e32 v[116:117], 0
	v_mov_b64_e32 v[118:119], 0
	v_mov_b64_e32 v[72:73], 0
	v_mov_b64_e32 v[74:75], 0
	v_mov_b64_e32 v[76:77], 0
	v_mov_b64_e32 v[78:79], 0
	v_mov_b64_e32 v[88:89], 0
	v_mov_b64_e32 v[90:91], 0
	v_mov_b64_e32 v[92:93], 0
	v_mov_b64_e32 v[94:95], 0
	v_mov_b64_e32 v[104:105], 0
	v_mov_b64_e32 v[106:107], 0
	v_mov_b64_e32 v[108:109], 0
	v_mov_b64_e32 v[110:111], 0
	v_mov_b64_e32 v[120:121], 0
	v_mov_b64_e32 v[122:123], 0
	v_mov_b64_e32 v[124:125], 0
	v_mov_b64_e32 v[126:127], 0
.Lz_skip_1:
	s_waitcnt vmcnt(8)
	s_waitcnt lgkmcnt(0)
	s_barrier
	s_waitcnt lgkmcnt(0)
	v_mfma_f32_16x16x32_bf16 v[124:127], v[128:131], v[186:189], v[124:127]
	v_mfma_f32_16x16x32_bf16 v[120:123], v[158:161], v[186:189], v[120:123]
	v_mfma_f32_16x16x32_bf16 v[108:111], v[128:131], v[194:197], v[108:111]
	v_mfma_f32_16x16x32_bf16 v[104:107], v[158:161], v[194:197], v[104:107]
	v_mfma_f32_16x16x32_bf16 v[92:95], v[128:131], v[202:205], v[92:95]
	v_mfma_f32_16x16x32_bf16 v[88:91], v[158:161], v[202:205], v[88:91]
	v_mfma_f32_16x16x32_bf16 v[76:79], v[128:131], v[222:225], v[76:79]
	v_mfma_f32_16x16x32_bf16 v[72:75], v[158:161], v[222:225], v[72:75]
	v_mfma_f32_16x16x32_bf16 v[124:127], v[132:135], v[190:193], v[124:127]
	v_mfma_f32_16x16x32_bf16 v[120:123], v[162:165], v[190:193], v[120:123]
	v_mfma_f32_16x16x32_bf16 v[108:111], v[132:135], v[198:201], v[108:111]
	v_mfma_f32_16x16x32_bf16 v[104:107], v[162:165], v[198:201], v[104:107]
	v_mfma_f32_16x16x32_bf16 v[92:95], v[132:135], v[218:221], v[92:95]
	v_mfma_f32_16x16x32_bf16 v[88:91], v[162:165], v[218:221], v[88:91]
	v_mfma_f32_16x16x32_bf16 v[76:79], v[132:135], v[226:229], v[76:79]
	v_mfma_f32_16x16x32_bf16 v[72:75], v[162:165], v[226:229], v[72:75]
	v_mfma_f32_16x16x32_bf16 v[116:119], v[170:173], v[186:189], v[116:119]
	v_mfma_f32_16x16x32_bf16 v[112:115], v[178:181], v[186:189], v[112:115]
	v_mfma_f32_16x16x32_bf16 v[100:103], v[170:173], v[194:197], v[100:103]
	v_mfma_f32_16x16x32_bf16 v[96:99], v[178:181], v[194:197], v[96:99]
	v_mfma_f32_16x16x32_bf16 v[84:87], v[170:173], v[202:205], v[84:87]
	v_mfma_f32_16x16x32_bf16 v[80:83], v[178:181], v[202:205], v[80:83]
	v_mfma_f32_16x16x32_bf16 v[68:71], v[170:173], v[222:225], v[68:71]
	v_mfma_f32_16x16x32_bf16 v[64:67], v[178:181], v[222:225], v[64:67]
	v_mfma_f32_16x16x32_bf16 v[116:119], v[174:177], v[190:193], v[116:119]
	v_mfma_f32_16x16x32_bf16 v[112:115], v[182:185], v[190:193], v[112:115]
	v_mfma_f32_16x16x32_bf16 v[100:103], v[174:177], v[198:201], v[100:103]
	v_mfma_f32_16x16x32_bf16 v[96:99], v[182:185], v[198:201], v[96:99]
	v_mfma_f32_16x16x32_bf16 v[84:87], v[174:177], v[218:221], v[84:87]
	v_mfma_f32_16x16x32_bf16 v[80:83], v[182:185], v[218:221], v[80:83]
	v_mfma_f32_16x16x32_bf16 v[68:71], v[174:177], v[226:229], v[68:71]
	v_mfma_f32_16x16x32_bf16 v[64:67], v[182:185], v[226:229], v[64:67]
	s_barrier
	s_add_i32 s4, s45, s49
	v_lshl_add_u64 v[146:147], s[2:3], 0, v[148:149]
	s_mov_b32 m0, s4
	ds_read_b128 v[186:189], v169 offset:16384
	ds_read_b128 v[190:193], v169 offset:17408
	ds_read_b128 v[194:197], v169 offset:18432
	ds_read_b128 v[198:201], v169 offset:19456
	ds_read_b128 v[202:205], v169 offset:20480
	ds_read_b128 v[218:221], v169 offset:21504
	ds_read_b128 v[222:225], v169 offset:22528
	ds_read_b128 v[226:229], v169 offset:23552
	global_load_lds_dwordx4 v[146:147], off
	s_add_i32 m0, s4, 0x2000
	s_add_u32 s4, s2, 0xb0000
	v_lshl_add_u64 v[154:155], s[2:3], 0, v[136:137]
	s_addc_u32 s5, s3, 0
	s_add_i32 s45, s62, s49
	global_load_lds_dwordx4 v[154:155], off
	v_lshl_add_u64 v[156:157], s[4:5], 0, v[148:149]
	s_mov_b32 m0, s45
	v_lshl_add_u64 v[166:167], s[8:9], 0, v[138:139]
	global_load_lds_dwordx4 v[156:157], off
	v_lshl_add_u64 v[156:157], s[4:5], 0, v[136:137]
	s_add_i32 m0, s45, 0x2000
	s_nop 0
	global_load_lds_dwordx4 v[156:157], off
	v_lshl_add_u64 v[156:157], s[8:9], 0, v[140:141]
	s_mov_b32 m0, s50
	s_nop 0
	global_load_lds_dwordx4 v[156:157], off
	s_mov_b32 m0, s51
	s_nop 0
	global_load_lds_dwordx4 v[166:167], off
	s_waitcnt vmcnt(8)
	s_waitcnt lgkmcnt(0)
	s_barrier
	s_waitcnt lgkmcnt(0)
	v_mfma_f32_16x16x32_bf16 v[60:63], v[128:131], v[186:189], v[60:63]
	v_mfma_f32_16x16x32_bf16 v[56:59], v[158:161], v[186:189], v[56:59]
	v_mfma_f32_16x16x32_bf16 v[44:47], v[128:131], v[194:197], v[44:47]
	v_mfma_f32_16x16x32_bf16 v[40:43], v[158:161], v[194:197], v[40:43]
	v_mfma_f32_16x16x32_bf16 v[28:31], v[128:131], v[202:205], v[28:31]
	v_mfma_f32_16x16x32_bf16 v[24:27], v[158:161], v[202:205], v[24:27]
	v_mfma_f32_16x16x32_bf16 v[12:15], v[128:131], v[222:225], v[12:15]
	v_mfma_f32_16x16x32_bf16 v[8:11], v[158:161], v[222:225], v[8:11]
	v_mfma_f32_16x16x32_bf16 v[60:63], v[132:135], v[190:193], v[60:63]
	v_mfma_f32_16x16x32_bf16 v[56:59], v[162:165], v[190:193], v[56:59]
	v_mfma_f32_16x16x32_bf16 v[44:47], v[132:135], v[198:201], v[44:47]
	v_mfma_f32_16x16x32_bf16 v[40:43], v[162:165], v[198:201], v[40:43]
	v_mfma_f32_16x16x32_bf16 v[28:31], v[132:135], v[218:221], v[28:31]
	v_mfma_f32_16x16x32_bf16 v[24:27], v[162:165], v[218:221], v[24:27]
	v_mfma_f32_16x16x32_bf16 v[12:15], v[132:135], v[226:229], v[12:15]
	v_mfma_f32_16x16x32_bf16 v[8:11], v[162:165], v[226:229], v[8:11]
	v_mfma_f32_16x16x32_bf16 v[52:55], v[170:173], v[186:189], v[52:55]
	v_mfma_f32_16x16x32_bf16 v[48:51], v[178:181], v[186:189], v[48:51]
	v_mfma_f32_16x16x32_bf16 v[36:39], v[170:173], v[194:197], v[36:39]
	v_mfma_f32_16x16x32_bf16 v[32:35], v[178:181], v[194:197], v[32:35]
	v_mfma_f32_16x16x32_bf16 v[20:23], v[170:173], v[202:205], v[20:23]
	v_mfma_f32_16x16x32_bf16 v[16:19], v[178:181], v[202:205], v[16:19]
	v_mfma_f32_16x16x32_bf16 v[4:7], v[170:173], v[222:225], v[4:7]
	v_mfma_f32_16x16x32_bf16 v[0:3], v[178:181], v[222:225], v[0:3]
	v_mfma_f32_16x16x32_bf16 v[52:55], v[174:177], v[190:193], v[52:55]
	v_mfma_f32_16x16x32_bf16 v[48:51], v[182:185], v[190:193], v[48:51]
	v_mfma_f32_16x16x32_bf16 v[36:39], v[174:177], v[198:201], v[36:39]
	v_mfma_f32_16x16x32_bf16 v[32:35], v[182:185], v[198:201], v[32:35]
	v_mfma_f32_16x16x32_bf16 v[20:23], v[174:177], v[218:221], v[20:23]
	v_mfma_f32_16x16x32_bf16 v[16:19], v[182:185], v[218:221], v[16:19]
	v_mfma_f32_16x16x32_bf16 v[4:7], v[174:177], v[226:229], v[4:7]
	v_mfma_f32_16x16x32_bf16 v[0:3], v[182:185], v[226:229], v[0:3]
	s_barrier
	s_add_i32 s45, 0, 0x18000
	v_add_u32_e32 v150, s45, v168
	s_add_i32 s62, 0, 0x1c000
	ds_read_b128 v[128:131], v150
	ds_read_b128 v[132:135], v150 offset:1024
	ds_read_b128 v[158:161], v150 offset:2048
	ds_read_b128 v[162:165], v150 offset:3072
	v_add_u32_e32 v150, s62, v168
	ds_read_b128 v[170:173], v150
	ds_read_b128 v[174:177], v150 offset:1024
	ds_read_b128 v[178:181], v150 offset:2048
	ds_read_b128 v[182:185], v150 offset:3072
	s_add_u32 s4, s8, 0xb0000
	s_addc_u32 s5, s9, 0
	s_mov_b32 m0, s52
	v_lshl_add_u64 v[212:213], s[4:5], 0, v[140:141]
	ds_read_b128 v[186:189], v169 offset:32768
	ds_read_b128 v[190:193], v169 offset:33792
	ds_read_b128 v[194:197], v169 offset:34816
	ds_read_b128 v[198:201], v169 offset:35840
	ds_read_b128 v[202:205], v169 offset:36864
	ds_read_b128 v[218:221], v169 offset:37888
	ds_read_b128 v[222:225], v169 offset:38912
	ds_read_b128 v[226:229], v169 offset:39936
	global_load_lds_dwordx4 v[212:213], off
	v_lshl_add_u64 v[212:213], s[4:5], 0, v[138:139]
	s_mov_b32 m0, s53
	s_nop 0
	global_load_lds_dwordx4 v[212:213], off
	s_waitcnt vmcnt(8)
	s_waitcnt lgkmcnt(0)
	s_barrier
	s_waitcnt lgkmcnt(0)
	v_mfma_f32_16x16x32_bf16 v[124:127], v[128:131], v[186:189], v[124:127]
	v_mfma_f32_16x16x32_bf16 v[120:123], v[158:161], v[186:189], v[120:123]
	v_mfma_f32_16x16x32_bf16 v[108:111], v[128:131], v[194:197], v[108:111]
	v_mfma_f32_16x16x32_bf16 v[104:107], v[158:161], v[194:197], v[104:107]
	v_mfma_f32_16x16x32_bf16 v[92:95], v[128:131], v[202:205], v[92:95]
	v_mfma_f32_16x16x32_bf16 v[88:91], v[158:161], v[202:205], v[88:91]
	v_mfma_f32_16x16x32_bf16 v[76:79], v[128:131], v[222:225], v[76:79]
	v_mfma_f32_16x16x32_bf16 v[72:75], v[158:161], v[222:225], v[72:75]
	v_mfma_f32_16x16x32_bf16 v[124:127], v[132:135], v[190:193], v[124:127]
	v_mfma_f32_16x16x32_bf16 v[120:123], v[162:165], v[190:193], v[120:123]
	v_mfma_f32_16x16x32_bf16 v[108:111], v[132:135], v[198:201], v[108:111]
	v_mfma_f32_16x16x32_bf16 v[104:107], v[162:165], v[198:201], v[104:107]
	v_mfma_f32_16x16x32_bf16 v[92:95], v[132:135], v[218:221], v[92:95]
	v_mfma_f32_16x16x32_bf16 v[88:91], v[162:165], v[218:221], v[88:91]
	v_mfma_f32_16x16x32_bf16 v[76:79], v[132:135], v[226:229], v[76:79]
	v_mfma_f32_16x16x32_bf16 v[72:75], v[162:165], v[226:229], v[72:75]
	v_mfma_f32_16x16x32_bf16 v[116:119], v[170:173], v[186:189], v[116:119]
	v_mfma_f32_16x16x32_bf16 v[112:115], v[178:181], v[186:189], v[112:115]
	v_mfma_f32_16x16x32_bf16 v[100:103], v[170:173], v[194:197], v[100:103]
	v_mfma_f32_16x16x32_bf16 v[96:99], v[178:181], v[194:197], v[96:99]
	v_mfma_f32_16x16x32_bf16 v[84:87], v[170:173], v[202:205], v[84:87]
	v_mfma_f32_16x16x32_bf16 v[80:83], v[178:181], v[202:205], v[80:83]
	v_mfma_f32_16x16x32_bf16 v[68:71], v[170:173], v[222:225], v[68:71]
	v_mfma_f32_16x16x32_bf16 v[64:67], v[178:181], v[222:225], v[64:67]
	v_mfma_f32_16x16x32_bf16 v[116:119], v[174:177], v[190:193], v[116:119]
	v_mfma_f32_16x16x32_bf16 v[112:115], v[182:185], v[190:193], v[112:115]
	v_mfma_f32_16x16x32_bf16 v[100:103], v[174:177], v[198:201], v[100:103]
	v_mfma_f32_16x16x32_bf16 v[96:99], v[182:185], v[198:201], v[96:99]
	v_mfma_f32_16x16x32_bf16 v[84:87], v[174:177], v[218:221], v[84:87]
	v_mfma_f32_16x16x32_bf16 v[80:83], v[182:185], v[218:221], v[80:83]
	v_mfma_f32_16x16x32_bf16 v[68:71], v[174:177], v[226:229], v[68:71]
	v_mfma_f32_16x16x32_bf16 v[64:67], v[182:185], v[226:229], v[64:67]
	s_barrier
	s_add_i32 s4, s45, s49
	v_lshl_add_u64 v[146:147], v[146:147], 0, s[28:29]
	s_mov_b32 m0, s4
	ds_read_b128 v[186:189], v169 offset:49152
	ds_read_b128 v[190:193], v169 offset:50176
	ds_read_b128 v[194:197], v169 offset:51200
	ds_read_b128 v[198:201], v169 offset:52224
	ds_read_b128 v[202:205], v169 offset:53248
	ds_read_b128 v[218:221], v169 offset:54272
	ds_read_b128 v[222:225], v169 offset:55296
	ds_read_b128 v[226:229], v169 offset:56320
	global_load_lds_dwordx4 v[146:147], off
	s_add_i32 m0, s4, 0x2000
	s_add_u32 s2, s2, 0xb0080
	v_lshl_add_u64 v[146:147], v[154:155], 0, s[28:29]
	s_addc_u32 s3, s3, 0
	s_add_i32 s4, s62, s49
	global_load_lds_dwordx4 v[146:147], off
	v_lshl_add_u64 v[146:147], s[2:3], 0, v[148:149]
	s_mov_b32 m0, s4
	s_nop 0
	global_load_lds_dwordx4 v[146:147], off
	v_lshl_add_u64 v[146:147], s[2:3], 0, v[136:137]
	s_add_i32 m0, s4, 0x2000
	s_nop 0
	global_load_lds_dwordx4 v[146:147], off
	v_lshl_add_u64 v[146:147], v[156:157], 0, s[28:29]
	s_mov_b32 m0, s57
	s_nop 0
	global_load_lds_dwordx4 v[146:147], off
	v_lshl_add_u64 v[146:147], v[166:167], 0, s[28:29]
	s_mov_b32 m0, s58
	s_nop 0
	global_load_lds_dwordx4 v[146:147], off
	s_waitcnt vmcnt(8)
	s_waitcnt lgkmcnt(0)
	s_barrier
	s_waitcnt lgkmcnt(0)
	v_mfma_f32_16x16x32_bf16 v[60:63], v[128:131], v[186:189], v[60:63]
	v_mfma_f32_16x16x32_bf16 v[56:59], v[158:161], v[186:189], v[56:59]
	v_mfma_f32_16x16x32_bf16 v[44:47], v[128:131], v[194:197], v[44:47]
	v_mfma_f32_16x16x32_bf16 v[40:43], v[158:161], v[194:197], v[40:43]
	v_mfma_f32_16x16x32_bf16 v[28:31], v[128:131], v[202:205], v[28:31]
	v_mfma_f32_16x16x32_bf16 v[24:27], v[158:161], v[202:205], v[24:27]
	v_mfma_f32_16x16x32_bf16 v[12:15], v[128:131], v[222:225], v[12:15]
	v_mfma_f32_16x16x32_bf16 v[8:11], v[158:161], v[222:225], v[8:11]
	v_mfma_f32_16x16x32_bf16 v[60:63], v[132:135], v[190:193], v[60:63]
	v_mfma_f32_16x16x32_bf16 v[56:59], v[162:165], v[190:193], v[56:59]
	v_mfma_f32_16x16x32_bf16 v[44:47], v[132:135], v[198:201], v[44:47]
	v_mfma_f32_16x16x32_bf16 v[40:43], v[162:165], v[198:201], v[40:43]
	v_mfma_f32_16x16x32_bf16 v[28:31], v[132:135], v[218:221], v[28:31]
	v_mfma_f32_16x16x32_bf16 v[24:27], v[162:165], v[218:221], v[24:27]
	v_mfma_f32_16x16x32_bf16 v[12:15], v[132:135], v[226:229], v[12:15]
	v_mfma_f32_16x16x32_bf16 v[8:11], v[162:165], v[226:229], v[8:11]
	v_mfma_f32_16x16x32_bf16 v[52:55], v[170:173], v[186:189], v[52:55]
	v_mfma_f32_16x16x32_bf16 v[48:51], v[178:181], v[186:189], v[48:51]
	v_mfma_f32_16x16x32_bf16 v[36:39], v[170:173], v[194:197], v[36:39]
	v_mfma_f32_16x16x32_bf16 v[32:35], v[178:181], v[194:197], v[32:35]
	v_mfma_f32_16x16x32_bf16 v[20:23], v[170:173], v[202:205], v[20:23]
	v_mfma_f32_16x16x32_bf16 v[16:19], v[178:181], v[202:205], v[16:19]
	v_mfma_f32_16x16x32_bf16 v[4:7], v[170:173], v[222:225], v[4:7]
	v_mfma_f32_16x16x32_bf16 v[0:3], v[178:181], v[222:225], v[0:3]
	v_mfma_f32_16x16x32_bf16 v[52:55], v[174:177], v[190:193], v[52:55]
	v_mfma_f32_16x16x32_bf16 v[48:51], v[182:185], v[190:193], v[48:51]
	v_mfma_f32_16x16x32_bf16 v[36:39], v[174:177], v[198:201], v[36:39]
	v_mfma_f32_16x16x32_bf16 v[32:35], v[182:185], v[198:201], v[32:35]
	v_mfma_f32_16x16x32_bf16 v[20:23], v[174:177], v[218:221], v[20:23]
	v_mfma_f32_16x16x32_bf16 v[16:19], v[182:185], v[218:221], v[16:19]
	v_mfma_f32_16x16x32_bf16 v[4:7], v[174:177], v[226:229], v[4:7]
	v_mfma_f32_16x16x32_bf16 v[0:3], v[182:185], v[226:229], v[0:3]
	s_barrier
	s_add_i32 s44, s44, 2
	s_add_u32 s42, s42, 0x100
	s_addc_u32 s43, s43, 0
	s_cmp_gt_u32 s44, 41
	s_mov_b64 s[4:5], s[0:1]
	s_cbranch_scc0 .LBB0_360
	s_and_b64 vcc, exec, s[30:31]
	s_cbranch_vccz .LBB0_363
	s_barrier

.LBB0_587:
	s_ashr_i32 s37, s36, 31
	s_lshl_b64 s[14:15], s[36:37], 19
	s_add_u32 s38, s90, s14
	s_addc_u32 s39, s91, s15
	s_and_b64 s[14:15], s[6:7], exec
	s_cselect_b32 s9, s39, s11
	s_cselect_b32 s16, s38, s10
	s_ashr_i32 s35, s34, 31
	s_lshl_b64 s[14:15], s[34:35], 19
	s_add_u32 s40, s0, s14
	s_addc_u32 s41, s1, s15
	s_and_b64 s[14:15], s[6:7], exec
	s_cselect_b32 s17, s41, s13
	s_cselect_b32 s35, s40, s12
	s_add_u32 s10, s10, 0x40080
	s_addc_u32 s11, s11, 0
	s_add_u32 s37, s12, 0x100
	s_addc_u32 s42, s13, 0
	s_mov_b32 s43, -2
	s_waitcnt lgkmcnt(0)
	.p2alignl 6, 3212836864
.LBB0_588:
	s_add_u32 s12, s10, 0xfffc0080
	s_addc_u32 s13, s11, -1
	s_add_i32 s44, 0, 0x10000
	s_cmp_eq_u32 s43, 12
	s_cselect_b32 s15, s9, s13
	s_cselect_b32 s14, s16, s12
	v_add_u32_e32 v146, s44, v144
	s_cselect_b32 s13, s17, s42
	s_cselect_b32 s12, s35, s37
	s_add_i32 s46, 0, 0x14000
	ds_read_b128 v[140:143], v146
	ds_read_b128 v[158:161], v146 offset:1024
	ds_read_b128 v[162:165], v146 offset:2048
	ds_read_b128 v[166:169], v146 offset:3072
	v_add_u32_e32 v146, s46, v144
	ds_read_b128 v[174:177], v146
	ds_read_b128 v[178:181], v146 offset:1024
	ds_read_b128 v[182:185], v146 offset:2048
	ds_read_b128 v[186:189], v146 offset:3072
	v_lshl_add_u64 v[146:147], s[10:11], 0, v[136:137]
	s_add_i32 m0, s57, 0xc000
	ds_read_b128 v[190:193], v145
	ds_read_b128 v[194:197], v145 offset:1024
	ds_read_b128 v[198:201], v145 offset:2048
	ds_read_b128 v[202:205], v145 offset:3072
	ds_read_b128 v[218:221], v145 offset:4096
	ds_read_b128 v[222:225], v145 offset:5120
	ds_read_b128 v[226:229], v145 offset:6144
	ds_read_b128 v[230:233], v145 offset:7168
	global_load_lds_dwordx4 v[146:147], off
	v_lshl_add_u64 v[146:147], s[10:11], 0, v[138:139]
	s_add_i32 m0, s57, 0xe000
	s_nop 0
	global_load_lds_dwordx4 v[146:147], off
	s_cmp_lg_u32 s43, -2
	s_cbranch_scc1 .Lz_skip_2
	v_mov_b64_e32 v[0:1], 0
	v_mov_b64_e32 v[2:3], 0
	v_mov_b64_e32 v[4:5], 0
	v_mov_b64_e32 v[6:7], 0
	v_mov_b64_e32 v[16:17], 0
	v_mov_b64_e32 v[18:19], 0
	v_mov_b64_e32 v[20:21], 0
	v_mov_b64_e32 v[22:23], 0
	v_mov_b64_e32 v[32:33], 0
	v_mov_b64_e32 v[34:35], 0
	v_mov_b64_e32 v[36:37], 0
	v_mov_b64_e32 v[38:39], 0
	v_mov_b64_e32 v[48:49], 0
	v_mov_b64_e32 v[50:51], 0
	v_mov_b64_e32 v[52:53], 0
	v_mov_b64_e32 v[54:55], 0
	v_mov_b64_e32 v[8:9], 0
	v_mov_b64_e32 v[10:11], 0
	v_mov_b64_e32 v[12:13], 0
	v_mov_b64_e32 v[14:15], 0
	v_mov_b64_e32 v[24:25], 0
	v_mov_b64_e32 v[26:27], 0
	v_mov_b64_e32 v[28:29], 0
	v_mov_b64_e32 v[30:31], 0
	v_mov_b64_e32 v[40:41], 0
	v_mov_b64_e32 v[42:43], 0
	v_mov_b64_e32 v[44:45], 0
	v_mov_b64_e32 v[46:47], 0
	v_mov_b64_e32 v[56:57], 0
	v_mov_b64_e32 v[58:59], 0
	v_mov_b64_e32 v[60:61], 0
	v_mov_b64_e32 v[62:63], 0
	v_mov_b64_e32 v[64:65], 0
	v_mov_b64_e32 v[66:67], 0
	v_mov_b64_e32 v[68:69], 0
	v_mov_b64_e32 v[70:71], 0
	v_mov_b64_e32 v[80:81], 0
	v_mov_b64_e32 v[82:83], 0
	v_mov_b64_e32 v[84:85], 0
	v_mov_b64_e32 v[86:87], 0
	v_mov_b64_e32 v[96:97], 0
	v_mov_b64_e32 v[98:99], 0
	v_mov_b64_e32 v[100:101], 0
	v_mov_b64_e32 v[102:103], 0
	v_mov_b64_e32 v[112:113], 0
	v_mov_b64_e32 v[114:115], 0
	v_mov_b64_e32 v[116:117], 0
	v_mov_b64_e32 v[118:119], 0
	v_mov_b64_e32 v[72:73], 0
	v_mov_b64_e32 v[74:75], 0
	v_mov_b64_e32 v[76:77], 0
	v_mov_b64_e32 v[78:79], 0
	v_mov_b64_e32 v[88:89], 0
	v_mov_b64_e32 v[90:91], 0
	v_mov_b64_e32 v[92:93], 0
	v_mov_b64_e32 v[94:95], 0
	v_mov_b64_e32 v[104:105], 0
	v_mov_b64_e32 v[106:107], 0
	v_mov_b64_e32 v[108:109], 0
	v_mov_b64_e32 v[110:111], 0
	v_mov_b64_e32 v[120:121], 0
	v_mov_b64_e32 v[122:123], 0
	v_mov_b64_e32 v[124:125], 0
	v_mov_b64_e32 v[126:127], 0
.Lz_skip_2:
	s_waitcnt vmcnt(8)
	s_waitcnt lgkmcnt(0)
	s_barrier
	s_waitcnt lgkmcnt(0)
	v_mfma_f32_16x16x32_bf16 v[124:127], v[140:143], v[190:193], v[124:127]
	v_mfma_f32_16x16x32_bf16 v[120:123], v[162:165], v[190:193], v[120:123]
	v_mfma_f32_16x16x32_bf16 v[108:111], v[140:143], v[198:201], v[108:111]
	v_mfma_f32_16x16x32_bf16 v[104:107], v[162:165], v[198:201], v[104:107]
	v_mfma_f32_16x16x32_bf16 v[92:95], v[140:143], v[218:221], v[92:95]
	v_mfma_f32_16x16x32_bf16 v[88:91], v[162:165], v[218:221], v[88:91]
	v_mfma_f32_16x16x32_bf16 v[76:79], v[140:143], v[226:229], v[76:79]
	v_mfma_f32_16x16x32_bf16 v[72:75], v[162:165], v[226:229], v[72:75]
	v_mfma_f32_16x16x32_bf16 v[124:127], v[158:161], v[194:197], v[124:127]
	v_mfma_f32_16x16x32_bf16 v[120:123], v[166:169], v[194:197], v[120:123]
	v_mfma_f32_16x16x32_bf16 v[108:111], v[158:161], v[202:205], v[108:111]
	v_mfma_f32_16x16x32_bf16 v[104:107], v[166:169], v[202:205], v[104:107]
	v_mfma_f32_16x16x32_bf16 v[92:95], v[158:161], v[222:225], v[92:95]
	v_mfma_f32_16x16x32_bf16 v[88:91], v[166:169], v[222:225], v[88:91]
	v_mfma_f32_16x16x32_bf16 v[76:79], v[158:161], v[230:233], v[76:79]
	v_mfma_f32_16x16x32_bf16 v[72:75], v[166:169], v[230:233], v[72:75]
	v_mfma_f32_16x16x32_bf16 v[116:119], v[174:177], v[190:193], v[116:119]
	v_mfma_f32_16x16x32_bf16 v[112:115], v[182:185], v[190:193], v[112:115]
	v_mfma_f32_16x16x32_bf16 v[100:103], v[174:177], v[198:201], v[100:103]
	v_mfma_f32_16x16x32_bf16 v[96:99], v[182:185], v[198:201], v[96:99]
	v_mfma_f32_16x16x32_bf16 v[84:87], v[174:177], v[218:221], v[84:87]
	v_mfma_f32_16x16x32_bf16 v[80:83], v[182:185], v[218:221], v[80:83]
	v_mfma_f32_16x16x32_bf16 v[68:71], v[174:177], v[226:229], v[68:71]
	v_mfma_f32_16x16x32_bf16 v[64:67], v[182:185], v[226:229], v[64:67]
	v_mfma_f32_16x16x32_bf16 v[116:119], v[178:181], v[194:197], v[116:119]
	v_mfma_f32_16x16x32_bf16 v[112:115], v[186:189], v[194:197], v[112:115]
	v_mfma_f32_16x16x32_bf16 v[100:103], v[178:181], v[202:205], v[100:103]
	v_mfma_f32_16x16x32_bf16 v[96:99], v[186:189], v[202:205], v[96:99]
	v_mfma_f32_16x16x32_bf16 v[84:87], v[178:181], v[222:225], v[84:87]
	v_mfma_f32_16x16x32_bf16 v[80:83], v[186:189], v[222:225], v[80:83]
	v_mfma_f32_16x16x32_bf16 v[68:71], v[178:181], v[230:233], v[68:71]
	v_mfma_f32_16x16x32_bf16 v[64:67], v[186:189], v[230:233], v[64:67]
	s_barrier
	s_add_i32 s44, s44, s56
	v_lshl_add_u64 v[146:147], s[12:13], 0, v[132:133]
	s_mov_b32 m0, s44
	ds_read_b128 v[190:193], v145 offset:16384
	ds_read_b128 v[194:197], v145 offset:17408
	ds_read_b128 v[198:201], v145 offset:18432
	ds_read_b128 v[202:205], v145 offset:19456
	ds_read_b128 v[218:221], v145 offset:20480
	ds_read_b128 v[222:225], v145 offset:21504
	ds_read_b128 v[226:229], v145 offset:22528
	ds_read_b128 v[230:233], v145 offset:23552
	global_load_lds_dwordx4 v[146:147], off
	s_add_i32 m0, s44, 0x2000
	s_add_u32 s44, s12, 0x40000
	v_lshl_add_u64 v[154:155], s[12:13], 0, v[128:129]
	s_addc_u32 s45, s13, 0
	s_add_i32 s46, s46, s56
	global_load_lds_dwordx4 v[154:155], off
	v_lshl_add_u64 v[156:157], s[44:45], 0, v[132:133]
	s_mov_b32 m0, s46
	v_lshl_add_u64 v[170:171], s[14:15], 0, v[130:131]
	global_load_lds_dwordx4 v[156:157], off
	v_lshl_add_u64 v[156:157], s[44:45], 0, v[128:129]
	s_add_i32 m0, s46, 0x2000
	s_nop 0
	global_load_lds_dwordx4 v[156:157], off
	v_lshl_add_u64 v[156:157], s[14:15], 0, v[134:135]
	s_mov_b32 m0, s57
	s_nop 0
	global_load_lds_dwordx4 v[156:157], off
	s_mov_b32 m0, s58
	s_nop 0
	global_load_lds_dwordx4 v[170:171], off
	s_waitcnt vmcnt(8)
	s_waitcnt lgkmcnt(0)
	s_barrier
	s_waitcnt lgkmcnt(0)
	v_mfma_f32_16x16x32_bf16 v[60:63], v[140:143], v[190:193], v[60:63]
	v_mfma_f32_16x16x32_bf16 v[56:59], v[162:165], v[190:193], v[56:59]
	v_mfma_f32_16x16x32_bf16 v[44:47], v[140:143], v[198:201], v[44:47]
	v_mfma_f32_16x16x32_bf16 v[40:43], v[162:165], v[198:201], v[40:43]
	v_mfma_f32_16x16x32_bf16 v[28:31], v[140:143], v[218:221], v[28:31]
	v_mfma_f32_16x16x32_bf16 v[24:27], v[162:165], v[218:221], v[24:27]
	v_mfma_f32_16x16x32_bf16 v[12:15], v[140:143], v[226:229], v[12:15]
	v_mfma_f32_16x16x32_bf16 v[8:11], v[162:165], v[226:229], v[8:11]
	v_mfma_f32_16x16x32_bf16 v[60:63], v[158:161], v[194:197], v[60:63]
	v_mfma_f32_16x16x32_bf16 v[56:59], v[166:169], v[194:197], v[56:59]
	v_mfma_f32_16x16x32_bf16 v[44:47], v[158:161], v[202:205], v[44:47]
	v_mfma_f32_16x16x32_bf16 v[40:43], v[166:169], v[202:205], v[40:43]
	v_mfma_f32_16x16x32_bf16 v[28:31], v[158:161], v[222:225], v[28:31]
	v_mfma_f32_16x16x32_bf16 v[24:27], v[166:169], v[222:225], v[24:27]
	v_mfma_f32_16x16x32_bf16 v[12:15], v[158:161], v[230:233], v[12:15]
	v_mfma_f32_16x16x32_bf16 v[8:11], v[166:169], v[230:233], v[8:11]
	v_mfma_f32_16x16x32_bf16 v[52:55], v[174:177], v[190:193], v[52:55]
	v_mfma_f32_16x16x32_bf16 v[48:51], v[182:185], v[190:193], v[48:51]
	v_mfma_f32_16x16x32_bf16 v[36:39], v[174:177], v[198:201], v[36:39]
	v_mfma_f32_16x16x32_bf16 v[32:35], v[182:185], v[198:201], v[32:35]
	v_mfma_f32_16x16x32_bf16 v[20:23], v[174:177], v[218:221], v[20:23]
	v_mfma_f32_16x16x32_bf16 v[16:19], v[182:185], v[218:221], v[16:19]
	v_mfma_f32_16x16x32_bf16 v[4:7], v[174:177], v[226:229], v[4:7]
	v_mfma_f32_16x16x32_bf16 v[0:3], v[182:185], v[226:229], v[0:3]
	v_mfma_f32_16x16x32_bf16 v[52:55], v[178:181], v[194:197], v[52:55]
	v_mfma_f32_16x16x32_bf16 v[48:51], v[186:189], v[194:197], v[48:51]
	v_mfma_f32_16x16x32_bf16 v[36:39], v[178:181], v[202:205], v[36:39]
	v_mfma_f32_16x16x32_bf16 v[32:35], v[186:189], v[202:205], v[32:35]
	v_mfma_f32_16x16x32_bf16 v[20:23], v[178:181], v[222:225], v[20:23]
	v_mfma_f32_16x16x32_bf16 v[16:19], v[186:189], v[222:225], v[16:19]
	v_mfma_f32_16x16x32_bf16 v[4:7], v[178:181], v[230:233], v[4:7]
	v_mfma_f32_16x16x32_bf16 v[0:3], v[186:189], v[230:233], v[0:3]
	s_barrier
	s_add_i32 s44, 0, 0x18000
	v_add_u32_e32 v148, s44, v144
	s_add_i32 s45, 0, 0x1c000
	ds_read_b128 v[140:143], v148
	ds_read_b128 v[158:161], v148 offset:1024
	ds_read_b128 v[162:165], v148 offset:2048
	ds_read_b128 v[166:169], v148 offset:3072
	v_add_u32_e32 v148, s45, v144
	ds_read_b128 v[174:177], v148
	ds_read_b128 v[178:181], v148 offset:1024
	ds_read_b128 v[182:185], v148 offset:2048
	ds_read_b128 v[186:189], v148 offset:3072
	s_add_u32 s14, s14, 0x40000
	s_addc_u32 s15, s15, 0
	s_mov_b32 m0, s59
	v_lshl_add_u64 v[212:213], s[14:15], 0, v[134:135]
	ds_read_b128 v[190:193], v145 offset:32768
	ds_read_b128 v[194:197], v145 offset:33792
	ds_read_b128 v[198:201], v145 offset:34816
	ds_read_b128 v[202:205], v145 offset:35840
	ds_read_b128 v[218:221], v145 offset:36864
	ds_read_b128 v[222:225], v145 offset:37888
	ds_read_b128 v[226:229], v145 offset:38912
	ds_read_b128 v[230:233], v145 offset:39936
	global_load_lds_dwordx4 v[212:213], off
	v_lshl_add_u64 v[212:213], s[14:15], 0, v[130:131]
	s_mov_b32 m0, s60
	s_nop 0
	global_load_lds_dwordx4 v[212:213], off
	s_waitcnt vmcnt(8)
	s_waitcnt lgkmcnt(0)
	s_barrier
	s_waitcnt lgkmcnt(0)
	v_mfma_f32_16x16x32_bf16 v[124:127], v[140:143], v[190:193], v[124:127]
	v_mfma_f32_16x16x32_bf16 v[120:123], v[162:165], v[190:193], v[120:123]
	v_mfma_f32_16x16x32_bf16 v[108:111], v[140:143], v[198:201], v[108:111]
	v_mfma_f32_16x16x32_bf16 v[104:107], v[162:165], v[198:201], v[104:107]
	v_mfma_f32_16x16x32_bf16 v[92:95], v[140:143], v[218:221], v[92:95]
	v_mfma_f32_16x16x32_bf16 v[88:91], v[162:165], v[218:221], v[88:91]
	v_mfma_f32_16x16x32_bf16 v[76:79], v[140:143], v[226:229], v[76:79]
	v_mfma_f32_16x16x32_bf16 v[72:75], v[162:165], v[226:229], v[72:75]
	v_mfma_f32_16x16x32_bf16 v[124:127], v[158:161], v[194:197], v[124:127]
	v_mfma_f32_16x16x32_bf16 v[120:123], v[166:169], v[194:197], v[120:123]
	v_mfma_f32_16x16x32_bf16 v[108:111], v[158:161], v[202:205], v[108:111]
	v_mfma_f32_16x16x32_bf16 v[104:107], v[166:169], v[202:205], v[104:107]
	v_mfma_f32_16x16x32_bf16 v[92:95], v[158:161], v[222:225], v[92:95]
	v_mfma_f32_16x16x32_bf16 v[88:91], v[166:169], v[222:225], v[88:91]
	v_mfma_f32_16x16x32_bf16 v[76:79], v[158:161], v[230:233], v[76:79]
	v_mfma_f32_16x16x32_bf16 v[72:75], v[166:169], v[230:233], v[72:75]
	v_mfma_f32_16x16x32_bf16 v[116:119], v[174:177], v[190:193], v[116:119]
	v_mfma_f32_16x16x32_bf16 v[112:115], v[182:185], v[190:193], v[112:115]
	v_mfma_f32_16x16x32_bf16 v[100:103], v[174:177], v[198:201], v[100:103]
	v_mfma_f32_16x16x32_bf16 v[96:99], v[182:185], v[198:201], v[96:99]
	v_mfma_f32_16x16x32_bf16 v[84:87], v[174:177], v[218:221], v[84:87]
	v_mfma_f32_16x16x32_bf16 v[80:83], v[182:185], v[218:221], v[80:83]
	v_mfma_f32_16x16x32_bf16 v[68:71], v[174:177], v[226:229], v[68:71]
	v_mfma_f32_16x16x32_bf16 v[64:67], v[182:185], v[226:229], v[64:67]
	v_mfma_f32_16x16x32_bf16 v[116:119], v[178:181], v[194:197], v[116:119]
	v_mfma_f32_16x16x32_bf16 v[112:115], v[186:189], v[194:197], v[112:115]
	v_mfma_f32_16x16x32_bf16 v[100:103], v[178:181], v[202:205], v[100:103]
	v_mfma_f32_16x16x32_bf16 v[96:99], v[186:189], v[202:205], v[96:99]
	v_mfma_f32_16x16x32_bf16 v[84:87], v[178:181], v[222:225], v[84:87]
	v_mfma_f32_16x16x32_bf16 v[80:83], v[186:189], v[222:225], v[80:83]
	v_mfma_f32_16x16x32_bf16 v[68:71], v[178:181], v[230:233], v[68:71]
	v_mfma_f32_16x16x32_bf16 v[64:67], v[186:189], v[230:233], v[64:67]
	s_barrier
	s_add_i32 s14, s44, s56
	v_lshl_add_u64 v[146:147], v[146:147], 0, s[28:29]
	s_mov_b32 m0, s14
	ds_read_b128 v[190:193], v145 offset:49152
	ds_read_b128 v[194:197], v145 offset:50176
	ds_read_b128 v[198:201], v145 offset:51200
	ds_read_b128 v[202:205], v145 offset:52224
	ds_read_b128 v[218:221], v145 offset:53248
	ds_read_b128 v[222:225], v145 offset:54272
	ds_read_b128 v[226:229], v145 offset:55296
	ds_read_b128 v[230:233], v145 offset:56320
	global_load_lds_dwordx4 v[146:147], off
	s_add_i32 m0, s14, 0x2000
	s_add_u32 s12, s12, 0x40080
	v_lshl_add_u64 v[146:147], v[154:155], 0, s[28:29]
	s_addc_u32 s13, s13, 0
	s_add_i32 s14, s45, s56
	global_load_lds_dwordx4 v[146:147], off
	v_lshl_add_u64 v[146:147], s[12:13], 0, v[132:133]
	s_mov_b32 m0, s14
	s_nop 0
	global_load_lds_dwordx4 v[146:147], off
	v_lshl_add_u64 v[146:147], s[12:13], 0, v[128:129]
	s_add_i32 m0, s14, 0x2000
	s_nop 0
	global_load_lds_dwordx4 v[146:147], off
	v_lshl_add_u64 v[146:147], v[156:157], 0, s[28:29]
	s_mov_b32 m0, s72
	s_nop 0
	global_load_lds_dwordx4 v[146:147], off
	v_lshl_add_u64 v[146:147], v[170:171], 0, s[28:29]
	s_mov_b32 m0, s73
	s_nop 0
	global_load_lds_dwordx4 v[146:147], off
	s_waitcnt vmcnt(8)
	s_waitcnt lgkmcnt(0)
	s_barrier
	s_waitcnt lgkmcnt(0)
	v_mfma_f32_16x16x32_bf16 v[60:63], v[140:143], v[190:193], v[60:63]
	v_mfma_f32_16x16x32_bf16 v[56:59], v[162:165], v[190:193], v[56:59]
	v_mfma_f32_16x16x32_bf16 v[44:47], v[140:143], v[198:201], v[44:47]
	v_mfma_f32_16x16x32_bf16 v[40:43], v[162:165], v[198:201], v[40:43]
	v_mfma_f32_16x16x32_bf16 v[28:31], v[140:143], v[218:221], v[28:31]
	v_mfma_f32_16x16x32_bf16 v[24:27], v[162:165], v[218:221], v[24:27]
	v_mfma_f32_16x16x32_bf16 v[12:15], v[140:143], v[226:229], v[12:15]
	v_mfma_f32_16x16x32_bf16 v[8:11], v[162:165], v[226:229], v[8:11]
	v_mfma_f32_16x16x32_bf16 v[60:63], v[158:161], v[194:197], v[60:63]
	v_mfma_f32_16x16x32_bf16 v[56:59], v[166:169], v[194:197], v[56:59]
	v_mfma_f32_16x16x32_bf16 v[44:47], v[158:161], v[202:205], v[44:47]
	v_mfma_f32_16x16x32_bf16 v[40:43], v[166:169], v[202:205], v[40:43]
	v_mfma_f32_16x16x32_bf16 v[28:31], v[158:161], v[222:225], v[28:31]
	v_mfma_f32_16x16x32_bf16 v[24:27], v[166:169], v[222:225], v[24:27]
	v_mfma_f32_16x16x32_bf16 v[12:15], v[158:161], v[230:233], v[12:15]
	v_mfma_f32_16x16x32_bf16 v[8:11], v[166:169], v[230:233], v[8:11]
	v_mfma_f32_16x16x32_bf16 v[52:55], v[174:177], v[190:193], v[52:55]
	v_mfma_f32_16x16x32_bf16 v[48:51], v[182:185], v[190:193], v[48:51]
	v_mfma_f32_16x16x32_bf16 v[36:39], v[174:177], v[198:201], v[36:39]
	v_mfma_f32_16x16x32_bf16 v[32:35], v[182:185], v[198:201], v[32:35]
	v_mfma_f32_16x16x32_bf16 v[20:23], v[174:177], v[218:221], v[20:23]
	v_mfma_f32_16x16x32_bf16 v[16:19], v[182:185], v[218:221], v[16:19]
	v_mfma_f32_16x16x32_bf16 v[4:7], v[174:177], v[226:229], v[4:7]
	v_mfma_f32_16x16x32_bf16 v[0:3], v[182:185], v[226:229], v[0:3]
	v_mfma_f32_16x16x32_bf16 v[52:55], v[178:181], v[194:197], v[52:55]
	v_mfma_f32_16x16x32_bf16 v[48:51], v[186:189], v[194:197], v[48:51]
	v_mfma_f32_16x16x32_bf16 v[36:39], v[178:181], v[202:205], v[36:39]
	v_mfma_f32_16x16x32_bf16 v[32:35], v[186:189], v[202:205], v[32:35]
	v_mfma_f32_16x16x32_bf16 v[20:23], v[178:181], v[222:225], v[20:23]
	v_mfma_f32_16x16x32_bf16 v[16:19], v[186:189], v[222:225], v[16:19]
	v_mfma_f32_16x16x32_bf16 v[4:7], v[178:181], v[230:233], v[4:7]
	v_mfma_f32_16x16x32_bf16 v[0:3], v[186:189], v[230:233], v[0:3]
	s_barrier
	s_add_i32 s43, s43, 2
	s_add_u32 s10, s10, 0x100
	s_addc_u32 s11, s11, 0
	s_add_u32 s37, s37, 0x100
	s_addc_u32 s42, s42, 0
	s_cmp_gt_u32 s43, 13
	s_cbranch_scc0 .LBB0_588
	s_and_b64 vcc, exec, s[26:27]
	s_cbranch_vccz .LBB0_591
	s_barrier

.LBB0_763:
	s_ashr_i32 s21, s20, 31
	s_lshl_b64 s[22:23], s[20:21], 19
	s_add_u32 s22, s10, s22
	s_addc_u32 s23, s11, s23
	s_and_b64 s[24:25], s[8:9], exec
	s_cselect_b32 s21, s23, s27
	s_cselect_b32 s48, s22, s26
	s_ashr_i32 s19, s18, 31
	s_lshl_b64 s[24:25], s[18:19], 19
	s_add_u32 s24, s90, s24
	s_addc_u32 s25, s91, s25
	s_and_b64 s[34:35], s[8:9], exec
	s_mov_b32 s57, s49
	s_cselect_b32 s19, s25, s31
	s_cselect_b32 s49, s24, s30
	s_add_u32 s26, s26, 0x40080
	s_addc_u32 s27, s27, 0
	s_add_u32 s50, s30, 0x100
	s_addc_u32 s51, s31, 0
	s_mov_b32 s52, -2
	.p2alignl 6, 3212836864
.LBB0_764:
	s_add_u32 s30, s26, 0xfffc0080
	s_addc_u32 s31, s27, -1
	s_add_i32 s53, 0, 0x10000
	s_cmp_eq_u32 s52, 12
	s_cselect_b32 s35, s21, s31
	s_cselect_b32 s34, s48, s30
	s_cselect_b32 s31, s19, s51
	s_cselect_b32 s30, s49, s50
	s_add_i32 s56, 0, 0x14000
	v_add_u32_e32 v140, s53, v173
	v_add_u32_e32 v150, s56, v173
	ds_read_b128 v[128:131], v140
	ds_read_b128 v[132:135], v140 offset:1024
	ds_read_b128 v[136:139], v140 offset:2048
	ds_read_b128 v[140:143], v140 offset:3072
	ds_read_b128 v[164:167], v150
	ds_read_b128 v[168:171], v150 offset:1024
	ds_read_b128 v[176:179], v150 offset:2048
	ds_read_b128 v[180:183], v150 offset:3072
	v_lshl_add_u64 v[154:155], s[26:27], 0, v[160:161]
	s_add_i32 m0, s37, 0xc000
	ds_read_b128 v[184:187], v174
	ds_read_b128 v[188:191], v174 offset:1024
	ds_read_b128 v[192:195], v174 offset:2048
	ds_read_b128 v[196:199], v174 offset:3072
	ds_read_b128 v[200:203], v174 offset:4096
	ds_read_b128 v[218:221], v174 offset:5120
	ds_read_b128 v[222:225], v174 offset:6144
	ds_read_b128 v[226:229], v174 offset:7168
	global_load_lds_dwordx4 v[154:155], off
	v_lshl_add_u64 v[154:155], s[26:27], 0, v[162:163]
	s_add_i32 m0, s37, 0xe000
	s_nop 0
	global_load_lds_dwordx4 v[154:155], off
	s_cmp_lg_u32 s52, -2
	s_cbranch_scc1 .Lz_skip_3
	v_mov_b64_e32 v[0:1], 0
	v_mov_b64_e32 v[2:3], 0
	v_mov_b64_e32 v[32:33], 0
	v_mov_b64_e32 v[34:35], 0
	v_mov_b64_e32 v[4:5], 0
	v_mov_b64_e32 v[6:7], 0
	v_mov_b64_e32 v[36:37], 0
	v_mov_b64_e32 v[38:39], 0
	v_mov_b64_e32 v[8:9], 0
	v_mov_b64_e32 v[10:11], 0
	v_mov_b64_e32 v[40:41], 0
	v_mov_b64_e32 v[42:43], 0
	v_mov_b64_e32 v[12:13], 0
	v_mov_b64_e32 v[14:15], 0
	v_mov_b64_e32 v[44:45], 0
	v_mov_b64_e32 v[46:47], 0
	v_mov_b64_e32 v[64:65], 0
	v_mov_b64_e32 v[66:67], 0
	v_mov_b64_e32 v[96:97], 0
	v_mov_b64_e32 v[98:99], 0
	v_mov_b64_e32 v[68:69], 0
	v_mov_b64_e32 v[70:71], 0
	v_mov_b64_e32 v[100:101], 0
	v_mov_b64_e32 v[102:103], 0
	v_mov_b64_e32 v[72:73], 0
	v_mov_b64_e32 v[74:75], 0
	v_mov_b64_e32 v[104:105], 0
	v_mov_b64_e32 v[106:107], 0
	v_mov_b64_e32 v[76:77], 0
	v_mov_b64_e32 v[78:79], 0
	v_mov_b64_e32 v[108:109], 0
	v_mov_b64_e32 v[110:111], 0
	v_mov_b64_e32 v[16:17], 0
	v_mov_b64_e32 v[18:19], 0
	v_mov_b64_e32 v[48:49], 0
	v_mov_b64_e32 v[50:51], 0
	v_mov_b64_e32 v[20:21], 0
	v_mov_b64_e32 v[22:23], 0
	v_mov_b64_e32 v[52:53], 0
	v_mov_b64_e32 v[54:55], 0
	v_mov_b64_e32 v[24:25], 0
	v_mov_b64_e32 v[26:27], 0
	v_mov_b64_e32 v[56:57], 0
	v_mov_b64_e32 v[58:59], 0
	v_mov_b64_e32 v[28:29], 0
	v_mov_b64_e32 v[30:31], 0
	v_mov_b64_e32 v[60:61], 0
	v_mov_b64_e32 v[62:63], 0
	v_mov_b64_e32 v[80:81], 0
	v_mov_b64_e32 v[82:83], 0
	v_mov_b64_e32 v[112:113], 0
	v_mov_b64_e32 v[114:115], 0
	v_mov_b64_e32 v[84:85], 0
	v_mov_b64_e32 v[86:87], 0
	v_mov_b64_e32 v[116:117], 0
	v_mov_b64_e32 v[118:119], 0
	v_mov_b64_e32 v[88:89], 0
	v_mov_b64_e32 v[90:91], 0
	v_mov_b64_e32 v[120:121], 0
	v_mov_b64_e32 v[122:123], 0
	v_mov_b64_e32 v[92:93], 0
	v_mov_b64_e32 v[94:95], 0
	v_mov_b64_e32 v[124:125], 0
	v_mov_b64_e32 v[126:127], 0
.Lz_skip_3:
	s_waitcnt vmcnt(8)
	s_waitcnt lgkmcnt(0)
	s_barrier
	s_waitcnt lgkmcnt(0)
	v_mfma_f32_16x16x32_bf16 v[124:127], v[128:131], v[184:187], v[124:127]
	v_mfma_f32_16x16x32_bf16 v[92:95], v[136:139], v[184:187], v[92:95]
	v_mfma_f32_16x16x32_bf16 v[120:123], v[128:131], v[192:195], v[120:123]
	v_mfma_f32_16x16x32_bf16 v[88:91], v[136:139], v[192:195], v[88:91]
	v_mfma_f32_16x16x32_bf16 v[116:119], v[128:131], v[200:203], v[116:119]
	v_mfma_f32_16x16x32_bf16 v[84:87], v[136:139], v[200:203], v[84:87]
	v_mfma_f32_16x16x32_bf16 v[112:115], v[128:131], v[222:225], v[112:115]
	v_mfma_f32_16x16x32_bf16 v[80:83], v[136:139], v[222:225], v[80:83]
	v_mfma_f32_16x16x32_bf16 v[124:127], v[132:135], v[188:191], v[124:127]
	v_mfma_f32_16x16x32_bf16 v[92:95], v[140:143], v[188:191], v[92:95]
	v_mfma_f32_16x16x32_bf16 v[120:123], v[132:135], v[196:199], v[120:123]
	v_mfma_f32_16x16x32_bf16 v[88:91], v[140:143], v[196:199], v[88:91]
	v_mfma_f32_16x16x32_bf16 v[116:119], v[132:135], v[218:221], v[116:119]
	v_mfma_f32_16x16x32_bf16 v[84:87], v[140:143], v[218:221], v[84:87]
	v_mfma_f32_16x16x32_bf16 v[112:115], v[132:135], v[226:229], v[112:115]
	v_mfma_f32_16x16x32_bf16 v[80:83], v[140:143], v[226:229], v[80:83]
	v_mfma_f32_16x16x32_bf16 v[60:63], v[164:167], v[184:187], v[60:63]
	v_mfma_f32_16x16x32_bf16 v[28:31], v[176:179], v[184:187], v[28:31]
	v_mfma_f32_16x16x32_bf16 v[56:59], v[164:167], v[192:195], v[56:59]
	v_mfma_f32_16x16x32_bf16 v[24:27], v[176:179], v[192:195], v[24:27]
	v_mfma_f32_16x16x32_bf16 v[52:55], v[164:167], v[200:203], v[52:55]
	v_mfma_f32_16x16x32_bf16 v[20:23], v[176:179], v[200:203], v[20:23]
	v_mfma_f32_16x16x32_bf16 v[48:51], v[164:167], v[222:225], v[48:51]
	v_mfma_f32_16x16x32_bf16 v[16:19], v[176:179], v[222:225], v[16:19]
	v_mfma_f32_16x16x32_bf16 v[60:63], v[168:171], v[188:191], v[60:63]
	v_mfma_f32_16x16x32_bf16 v[28:31], v[180:183], v[188:191], v[28:31]
	v_mfma_f32_16x16x32_bf16 v[56:59], v[168:171], v[196:199], v[56:59]
	v_mfma_f32_16x16x32_bf16 v[24:27], v[180:183], v[196:199], v[24:27]
	v_mfma_f32_16x16x32_bf16 v[52:55], v[168:171], v[218:221], v[52:55]
	v_mfma_f32_16x16x32_bf16 v[20:23], v[180:183], v[218:221], v[20:23]
	v_mfma_f32_16x16x32_bf16 v[48:51], v[168:171], v[226:229], v[48:51]
	v_mfma_f32_16x16x32_bf16 v[16:19], v[180:183], v[226:229], v[16:19]
	s_barrier
	s_add_i32 s53, s53, s36
	v_lshl_add_u64 v[154:155], s[30:31], 0, v[158:159]
	s_mov_b32 m0, s53
	ds_read_b128 v[184:187], v174 offset:16384
	ds_read_b128 v[188:191], v174 offset:17408
	ds_read_b128 v[192:195], v174 offset:18432
	ds_read_b128 v[196:199], v174 offset:19456
	ds_read_b128 v[200:203], v174 offset:20480
	ds_read_b128 v[218:221], v174 offset:21504
	ds_read_b128 v[222:225], v174 offset:22528
	ds_read_b128 v[226:229], v174 offset:23552
	global_load_lds_dwordx4 v[154:155], off
	s_add_i32 m0, s53, 0x2000
	s_add_u32 s54, s30, 0x40000
	v_lshl_add_u64 v[156:157], s[30:31], 0, v[144:145]
	s_addc_u32 s55, s31, 0
	s_add_i32 s53, s56, s36
	global_load_lds_dwordx4 v[156:157], off
	v_lshl_add_u64 v[204:205], s[54:55], 0, v[158:159]
	s_mov_b32 m0, s53
	v_lshl_add_u64 v[212:213], s[34:35], 0, v[146:147]
	global_load_lds_dwordx4 v[204:205], off
	v_lshl_add_u64 v[204:205], s[54:55], 0, v[144:145]
	s_add_i32 m0, s53, 0x2000
	s_nop 0
	global_load_lds_dwordx4 v[204:205], off
	v_lshl_add_u64 v[204:205], s[34:35], 0, v[148:149]
	s_mov_b32 m0, s37
	s_nop 0
	global_load_lds_dwordx4 v[204:205], off
	s_mov_b32 m0, s38
	s_nop 0
	global_load_lds_dwordx4 v[212:213], off
	s_waitcnt vmcnt(8)
	s_waitcnt lgkmcnt(0)
	s_barrier
	s_waitcnt lgkmcnt(0)
	v_mfma_f32_16x16x32_bf16 v[108:111], v[128:131], v[184:187], v[108:111]
	v_mfma_f32_16x16x32_bf16 v[76:79], v[136:139], v[184:187], v[76:79]
	v_mfma_f32_16x16x32_bf16 v[104:107], v[128:131], v[192:195], v[104:107]
	v_mfma_f32_16x16x32_bf16 v[72:75], v[136:139], v[192:195], v[72:75]
	v_mfma_f32_16x16x32_bf16 v[100:103], v[128:131], v[200:203], v[100:103]
	v_mfma_f32_16x16x32_bf16 v[68:71], v[136:139], v[200:203], v[68:71]
	v_mfma_f32_16x16x32_bf16 v[96:99], v[128:131], v[222:225], v[96:99]
	v_mfma_f32_16x16x32_bf16 v[64:67], v[136:139], v[222:225], v[64:67]
	v_mfma_f32_16x16x32_bf16 v[108:111], v[132:135], v[188:191], v[108:111]
	v_mfma_f32_16x16x32_bf16 v[76:79], v[140:143], v[188:191], v[76:79]
	v_mfma_f32_16x16x32_bf16 v[104:107], v[132:135], v[196:199], v[104:107]
	v_mfma_f32_16x16x32_bf16 v[72:75], v[140:143], v[196:199], v[72:75]
	v_mfma_f32_16x16x32_bf16 v[100:103], v[132:135], v[218:221], v[100:103]
	v_mfma_f32_16x16x32_bf16 v[68:71], v[140:143], v[218:221], v[68:71]
	v_mfma_f32_16x16x32_bf16 v[96:99], v[132:135], v[226:229], v[96:99]
	v_mfma_f32_16x16x32_bf16 v[64:67], v[140:143], v[226:229], v[64:67]
	v_mfma_f32_16x16x32_bf16 v[44:47], v[164:167], v[184:187], v[44:47]
	v_mfma_f32_16x16x32_bf16 v[12:15], v[176:179], v[184:187], v[12:15]
	v_mfma_f32_16x16x32_bf16 v[40:43], v[164:167], v[192:195], v[40:43]
	v_mfma_f32_16x16x32_bf16 v[8:11], v[176:179], v[192:195], v[8:11]
	v_mfma_f32_16x16x32_bf16 v[36:39], v[164:167], v[200:203], v[36:39]
	v_mfma_f32_16x16x32_bf16 v[4:7], v[176:179], v[200:203], v[4:7]
	v_mfma_f32_16x16x32_bf16 v[32:35], v[164:167], v[222:225], v[32:35]
	v_mfma_f32_16x16x32_bf16 v[0:3], v[176:179], v[222:225], v[0:3]
	v_mfma_f32_16x16x32_bf16 v[44:47], v[168:171], v[188:191], v[44:47]
	v_mfma_f32_16x16x32_bf16 v[12:15], v[180:183], v[188:191], v[12:15]
	v_mfma_f32_16x16x32_bf16 v[40:43], v[168:171], v[196:199], v[40:43]
	v_mfma_f32_16x16x32_bf16 v[8:11], v[180:183], v[196:199], v[8:11]
	v_mfma_f32_16x16x32_bf16 v[36:39], v[168:171], v[218:221], v[36:39]
	v_mfma_f32_16x16x32_bf16 v[4:7], v[180:183], v[218:221], v[4:7]
	v_mfma_f32_16x16x32_bf16 v[32:35], v[168:171], v[226:229], v[32:35]
	v_mfma_f32_16x16x32_bf16 v[0:3], v[180:183], v[226:229], v[0:3]
	s_barrier
	s_add_i32 s53, 0, 0x18000
	s_add_i32 s54, 0, 0x1c000
	v_add_u32_e32 v140, s53, v173
	v_add_u32_e32 v150, s54, v173
	ds_read_b128 v[128:131], v140
	ds_read_b128 v[132:135], v140 offset:1024
	ds_read_b128 v[136:139], v140 offset:2048
	ds_read_b128 v[140:143], v140 offset:3072
	ds_read_b128 v[164:167], v150
	ds_read_b128 v[168:171], v150 offset:1024
	ds_read_b128 v[176:179], v150 offset:2048
	ds_read_b128 v[180:183], v150 offset:3072
	s_add_u32 s34, s34, 0x40000
	s_addc_u32 s35, s35, 0
	s_mov_b32 m0, s39
	v_lshl_add_u64 v[214:215], s[34:35], 0, v[148:149]
	ds_read_b128 v[184:187], v174 offset:32768
	ds_read_b128 v[188:191], v174 offset:33792
	ds_read_b128 v[192:195], v174 offset:34816
	ds_read_b128 v[196:199], v174 offset:35840
	ds_read_b128 v[200:203], v174 offset:36864
	ds_read_b128 v[218:221], v174 offset:37888
	ds_read_b128 v[222:225], v174 offset:38912
	ds_read_b128 v[226:229], v174 offset:39936
	global_load_lds_dwordx4 v[214:215], off
	v_lshl_add_u64 v[214:215], s[34:35], 0, v[146:147]
	s_mov_b32 m0, s40
	s_nop 0
	global_load_lds_dwordx4 v[214:215], off
	s_waitcnt vmcnt(8)
	s_waitcnt lgkmcnt(0)
	s_barrier
	s_waitcnt lgkmcnt(0)
	v_mfma_f32_16x16x32_bf16 v[124:127], v[128:131], v[184:187], v[124:127]
	v_mfma_f32_16x16x32_bf16 v[92:95], v[136:139], v[184:187], v[92:95]
	v_mfma_f32_16x16x32_bf16 v[120:123], v[128:131], v[192:195], v[120:123]
	v_mfma_f32_16x16x32_bf16 v[88:91], v[136:139], v[192:195], v[88:91]
	v_mfma_f32_16x16x32_bf16 v[116:119], v[128:131], v[200:203], v[116:119]
	v_mfma_f32_16x16x32_bf16 v[84:87], v[136:139], v[200:203], v[84:87]
	v_mfma_f32_16x16x32_bf16 v[112:115], v[128:131], v[222:225], v[112:115]
	v_mfma_f32_16x16x32_bf16 v[80:83], v[136:139], v[222:225], v[80:83]
	v_mfma_f32_16x16x32_bf16 v[124:127], v[132:135], v[188:191], v[124:127]
	v_mfma_f32_16x16x32_bf16 v[92:95], v[140:143], v[188:191], v[92:95]
	v_mfma_f32_16x16x32_bf16 v[120:123], v[132:135], v[196:199], v[120:123]
	v_mfma_f32_16x16x32_bf16 v[88:91], v[140:143], v[196:199], v[88:91]
	v_mfma_f32_16x16x32_bf16 v[116:119], v[132:135], v[218:221], v[116:119]
	v_mfma_f32_16x16x32_bf16 v[84:87], v[140:143], v[218:221], v[84:87]
	v_mfma_f32_16x16x32_bf16 v[112:115], v[132:135], v[226:229], v[112:115]
	v_mfma_f32_16x16x32_bf16 v[80:83], v[140:143], v[226:229], v[80:83]
	v_mfma_f32_16x16x32_bf16 v[60:63], v[164:167], v[184:187], v[60:63]
	v_mfma_f32_16x16x32_bf16 v[28:31], v[176:179], v[184:187], v[28:31]
	v_mfma_f32_16x16x32_bf16 v[56:59], v[164:167], v[192:195], v[56:59]
	v_mfma_f32_16x16x32_bf16 v[24:27], v[176:179], v[192:195], v[24:27]
	v_mfma_f32_16x16x32_bf16 v[52:55], v[164:167], v[200:203], v[52:55]
	v_mfma_f32_16x16x32_bf16 v[20:23], v[176:179], v[200:203], v[20:23]
	v_mfma_f32_16x16x32_bf16 v[48:51], v[164:167], v[222:225], v[48:51]
	v_mfma_f32_16x16x32_bf16 v[16:19], v[176:179], v[222:225], v[16:19]
	v_mfma_f32_16x16x32_bf16 v[60:63], v[168:171], v[188:191], v[60:63]
	v_mfma_f32_16x16x32_bf16 v[28:31], v[180:183], v[188:191], v[28:31]
	v_mfma_f32_16x16x32_bf16 v[56:59], v[168:171], v[196:199], v[56:59]
	v_mfma_f32_16x16x32_bf16 v[24:27], v[180:183], v[196:199], v[24:27]
	v_mfma_f32_16x16x32_bf16 v[52:55], v[168:171], v[218:221], v[52:55]
	v_mfma_f32_16x16x32_bf16 v[20:23], v[180:183], v[218:221], v[20:23]
	v_mfma_f32_16x16x32_bf16 v[48:51], v[168:171], v[226:229], v[48:51]
	v_mfma_f32_16x16x32_bf16 v[16:19], v[180:183], v[226:229], v[16:19]
	s_barrier
	s_add_i32 s34, s53, s36
	v_lshl_add_u64 v[154:155], v[154:155], 0, s[28:29]
	s_mov_b32 m0, s34
	ds_read_b128 v[184:187], v174 offset:49152
	ds_read_b128 v[188:191], v174 offset:50176
	ds_read_b128 v[192:195], v174 offset:51200
	ds_read_b128 v[196:199], v174 offset:52224
	ds_read_b128 v[200:203], v174 offset:53248
	ds_read_b128 v[218:221], v174 offset:54272
	ds_read_b128 v[222:225], v174 offset:55296
	ds_read_b128 v[226:229], v174 offset:56320
	global_load_lds_dwordx4 v[154:155], off
	s_add_i32 m0, s34, 0x2000
	s_add_u32 s30, s30, 0x40080
	v_lshl_add_u64 v[154:155], v[156:157], 0, s[28:29]
	s_addc_u32 s31, s31, 0
	s_add_i32 s34, s54, s36
	global_load_lds_dwordx4 v[154:155], off
	v_lshl_add_u64 v[154:155], s[30:31], 0, v[158:159]
	s_mov_b32 m0, s34
	s_nop 0
	global_load_lds_dwordx4 v[154:155], off
	v_lshl_add_u64 v[154:155], s[30:31], 0, v[144:145]
	s_add_i32 m0, s34, 0x2000
	s_nop 0
	global_load_lds_dwordx4 v[154:155], off
	v_lshl_add_u64 v[154:155], v[204:205], 0, s[28:29]
	s_mov_b32 m0, s43
	s_nop 0
	global_load_lds_dwordx4 v[154:155], off
	v_lshl_add_u64 v[154:155], v[212:213], 0, s[28:29]
	s_mov_b32 m0, s44
	s_nop 0
	global_load_lds_dwordx4 v[154:155], off
	s_waitcnt vmcnt(8)
	s_waitcnt lgkmcnt(0)
	s_barrier
	s_waitcnt lgkmcnt(0)
	v_mfma_f32_16x16x32_bf16 v[108:111], v[128:131], v[184:187], v[108:111]
	v_mfma_f32_16x16x32_bf16 v[76:79], v[136:139], v[184:187], v[76:79]
	v_mfma_f32_16x16x32_bf16 v[104:107], v[128:131], v[192:195], v[104:107]
	v_mfma_f32_16x16x32_bf16 v[72:75], v[136:139], v[192:195], v[72:75]
	v_mfma_f32_16x16x32_bf16 v[100:103], v[128:131], v[200:203], v[100:103]
	v_mfma_f32_16x16x32_bf16 v[68:71], v[136:139], v[200:203], v[68:71]
	v_mfma_f32_16x16x32_bf16 v[96:99], v[128:131], v[222:225], v[96:99]
	v_mfma_f32_16x16x32_bf16 v[64:67], v[136:139], v[222:225], v[64:67]
	v_mfma_f32_16x16x32_bf16 v[108:111], v[132:135], v[188:191], v[108:111]
	v_mfma_f32_16x16x32_bf16 v[76:79], v[140:143], v[188:191], v[76:79]
	v_mfma_f32_16x16x32_bf16 v[104:107], v[132:135], v[196:199], v[104:107]
	v_mfma_f32_16x16x32_bf16 v[72:75], v[140:143], v[196:199], v[72:75]
	v_mfma_f32_16x16x32_bf16 v[100:103], v[132:135], v[218:221], v[100:103]
	v_mfma_f32_16x16x32_bf16 v[68:71], v[140:143], v[218:221], v[68:71]
	v_mfma_f32_16x16x32_bf16 v[96:99], v[132:135], v[226:229], v[96:99]
	v_mfma_f32_16x16x32_bf16 v[64:67], v[140:143], v[226:229], v[64:67]
	v_mfma_f32_16x16x32_bf16 v[44:47], v[164:167], v[184:187], v[44:47]
	v_mfma_f32_16x16x32_bf16 v[12:15], v[176:179], v[184:187], v[12:15]
	v_mfma_f32_16x16x32_bf16 v[40:43], v[164:167], v[192:195], v[40:43]
	v_mfma_f32_16x16x32_bf16 v[8:11], v[176:179], v[192:195], v[8:11]
	v_mfma_f32_16x16x32_bf16 v[36:39], v[164:167], v[200:203], v[36:39]
	v_mfma_f32_16x16x32_bf16 v[4:7], v[176:179], v[200:203], v[4:7]
	v_mfma_f32_16x16x32_bf16 v[32:35], v[164:167], v[222:225], v[32:35]
	v_mfma_f32_16x16x32_bf16 v[0:3], v[176:179], v[222:225], v[0:3]
	v_mfma_f32_16x16x32_bf16 v[44:47], v[168:171], v[188:191], v[44:47]
	v_mfma_f32_16x16x32_bf16 v[12:15], v[180:183], v[188:191], v[12:15]
	v_mfma_f32_16x16x32_bf16 v[40:43], v[168:171], v[196:199], v[40:43]
	v_mfma_f32_16x16x32_bf16 v[8:11], v[180:183], v[196:199], v[8:11]
	v_mfma_f32_16x16x32_bf16 v[36:39], v[168:171], v[218:221], v[36:39]
	v_mfma_f32_16x16x32_bf16 v[4:7], v[180:183], v[218:221], v[4:7]
	v_mfma_f32_16x16x32_bf16 v[32:35], v[168:171], v[226:229], v[32:35]
	v_mfma_f32_16x16x32_bf16 v[0:3], v[180:183], v[226:229], v[0:3]
	s_barrier
	s_add_i32 s52, s52, 2
	s_add_u32 s26, s26, 0x100
	s_addc_u32 s27, s27, 0
	s_add_u32 s50, s50, 0x100
	s_addc_u32 s51, s51, 0
	s_cmp_gt_u32 s52, 13
	s_cbranch_scc0 .LBB0_764
	s_and_b64 vcc, exec, s[16:17]
	s_mov_b32 s49, s57
	s_cbranch_vccz .LBB0_767
	s_barrier

.LBB0_1334:
	s_ashr_i32 s17, s16, 31
	s_lshl_b64 s[18:19], s[16:17], 18
	s_add_u32 s18, s33, s18
	s_addc_u32 s19, s34, s19
	s_and_b64 s[20:21], s[6:7], exec
	s_cselect_b32 s17, s19, s9
	s_cselect_b32 s49, s18, s8
	s_ashr_i32 s15, s14, 31
	s_lshl_b64 s[20:21], s[14:15], 18
	s_add_u32 s20, s35, s20
	s_addc_u32 s21, s36, s21
	s_and_b64 s[24:25], s[6:7], exec
	s_cselect_b32 s15, s21, s23
	s_cselect_b32 s50, s20, s22
	s_add_u32 s8, s8, 0x20080
	s_addc_u32 s9, s9, 0
	s_add_u32 s51, s22, 0x100
	s_addc_u32 s52, s23, 0
	s_mov_b32 s53, -2
	.p2alignl 6, 3212836864
.LBB0_1335:
	s_add_u32 s22, s8, 0xfffe0080
	s_addc_u32 s23, s9, -1
	s_add_i32 s54, 0, 0x10000
	s_cmp_eq_u32 s53, 4
	s_cselect_b32 s25, s17, s23
	s_cselect_b32 s24, s49, s22
	v_add_u32_e32 v146, s54, v158
	s_cselect_b32 s23, s15, s52
	s_cselect_b32 s22, s50, s51
	s_add_i32 s56, 0, 0x14000
	ds_read_b128 v[138:141], v146
	ds_read_b128 v[142:145], v146 offset:1024
	ds_read_b128 v[154:157], v146 offset:2048
	ds_read_b128 v[160:163], v146 offset:3072
	v_add_u32_e32 v146, s56, v158
	ds_read_b128 v[164:167], v146
	ds_read_b128 v[168:171], v146 offset:1024
	ds_read_b128 v[172:175], v146 offset:2048
	ds_read_b128 v[176:179], v146 offset:3072
	v_lshl_add_u64 v[146:147], s[8:9], 0, v[134:135]
	s_add_i32 m0, s38, 0xc000
	ds_read_b128 v[180:183], v159
	ds_read_b128 v[184:187], v159 offset:1024
	ds_read_b128 v[188:191], v159 offset:2048
	ds_read_b128 v[192:195], v159 offset:3072
	ds_read_b128 v[196:199], v159 offset:4096
	ds_read_b128 v[200:203], v159 offset:5120
	ds_read_b128 v[212:215], v159 offset:6144
	ds_read_b128 v[220:223], v159 offset:7168
	global_load_lds_dwordx4 v[146:147], off
	v_lshl_add_u64 v[146:147], s[8:9], 0, v[136:137]
	s_add_i32 m0, s38, 0xe000
	s_nop 0
	global_load_lds_dwordx4 v[146:147], off
	s_cmp_lg_u32 s53, -2
	s_cbranch_scc1 .Lz_skip_4
	v_mov_b64_e32 v[0:1], 0
	v_mov_b64_e32 v[2:3], 0
	v_mov_b64_e32 v[4:5], 0
	v_mov_b64_e32 v[6:7], 0
	v_mov_b64_e32 v[16:17], 0
	v_mov_b64_e32 v[18:19], 0
	v_mov_b64_e32 v[20:21], 0
	v_mov_b64_e32 v[22:23], 0
	v_mov_b64_e32 v[32:33], 0
	v_mov_b64_e32 v[34:35], 0
	v_mov_b64_e32 v[36:37], 0
	v_mov_b64_e32 v[38:39], 0
	v_mov_b64_e32 v[48:49], 0
	v_mov_b64_e32 v[50:51], 0
	v_mov_b64_e32 v[52:53], 0
	v_mov_b64_e32 v[54:55], 0
	v_mov_b64_e32 v[8:9], 0
	v_mov_b64_e32 v[10:11], 0
	v_mov_b64_e32 v[12:13], 0
	v_mov_b64_e32 v[14:15], 0
	v_mov_b64_e32 v[24:25], 0
	v_mov_b64_e32 v[26:27], 0
	v_mov_b64_e32 v[28:29], 0
	v_mov_b64_e32 v[30:31], 0
	v_mov_b64_e32 v[40:41], 0
	v_mov_b64_e32 v[42:43], 0
	v_mov_b64_e32 v[44:45], 0
	v_mov_b64_e32 v[46:47], 0
	v_mov_b64_e32 v[56:57], 0
	v_mov_b64_e32 v[58:59], 0
	v_mov_b64_e32 v[60:61], 0
	v_mov_b64_e32 v[62:63], 0
	v_mov_b64_e32 v[64:65], 0
	v_mov_b64_e32 v[66:67], 0
	v_mov_b64_e32 v[68:69], 0
	v_mov_b64_e32 v[70:71], 0
	v_mov_b64_e32 v[80:81], 0
	v_mov_b64_e32 v[82:83], 0
	v_mov_b64_e32 v[84:85], 0
	v_mov_b64_e32 v[86:87], 0
	v_mov_b64_e32 v[96:97], 0
	v_mov_b64_e32 v[98:99], 0
	v_mov_b64_e32 v[100:101], 0
	v_mov_b64_e32 v[102:103], 0
	v_mov_b64_e32 v[112:113], 0
	v_mov_b64_e32 v[114:115], 0
	v_mov_b64_e32 v[116:117], 0
	v_mov_b64_e32 v[118:119], 0
	v_mov_b64_e32 v[72:73], 0
	v_mov_b64_e32 v[74:75], 0
	v_mov_b64_e32 v[76:77], 0
	v_mov_b64_e32 v[78:79], 0
	v_mov_b64_e32 v[88:89], 0
	v_mov_b64_e32 v[90:91], 0
	v_mov_b64_e32 v[92:93], 0
	v_mov_b64_e32 v[94:95], 0
	v_mov_b64_e32 v[104:105], 0
	v_mov_b64_e32 v[106:107], 0
	v_mov_b64_e32 v[108:109], 0
	v_mov_b64_e32 v[110:111], 0
	v_mov_b64_e32 v[120:121], 0
	v_mov_b64_e32 v[122:123], 0
	v_mov_b64_e32 v[124:125], 0
	v_mov_b64_e32 v[126:127], 0
.Lz_skip_4:
	s_waitcnt vmcnt(8)
	s_waitcnt lgkmcnt(0)
	s_barrier
	s_waitcnt lgkmcnt(0)
	v_mfma_f32_16x16x32_bf16 v[124:127], v[138:141], v[180:183], v[124:127]
	v_mfma_f32_16x16x32_bf16 v[120:123], v[154:157], v[180:183], v[120:123]
	v_mfma_f32_16x16x32_bf16 v[108:111], v[138:141], v[188:191], v[108:111]
	v_mfma_f32_16x16x32_bf16 v[104:107], v[154:157], v[188:191], v[104:107]
	v_mfma_f32_16x16x32_bf16 v[92:95], v[138:141], v[196:199], v[92:95]
	v_mfma_f32_16x16x32_bf16 v[88:91], v[154:157], v[196:199], v[88:91]
	v_mfma_f32_16x16x32_bf16 v[76:79], v[138:141], v[212:215], v[76:79]
	v_mfma_f32_16x16x32_bf16 v[72:75], v[154:157], v[212:215], v[72:75]
	v_mfma_f32_16x16x32_bf16 v[124:127], v[142:145], v[184:187], v[124:127]
	v_mfma_f32_16x16x32_bf16 v[120:123], v[160:163], v[184:187], v[120:123]
	v_mfma_f32_16x16x32_bf16 v[108:111], v[142:145], v[192:195], v[108:111]
	v_mfma_f32_16x16x32_bf16 v[104:107], v[160:163], v[192:195], v[104:107]
	v_mfma_f32_16x16x32_bf16 v[92:95], v[142:145], v[200:203], v[92:95]
	v_mfma_f32_16x16x32_bf16 v[88:91], v[160:163], v[200:203], v[88:91]
	v_mfma_f32_16x16x32_bf16 v[76:79], v[142:145], v[220:223], v[76:79]
	v_mfma_f32_16x16x32_bf16 v[72:75], v[160:163], v[220:223], v[72:75]
	v_mfma_f32_16x16x32_bf16 v[116:119], v[164:167], v[180:183], v[116:119]
	v_mfma_f32_16x16x32_bf16 v[112:115], v[172:175], v[180:183], v[112:115]
	v_mfma_f32_16x16x32_bf16 v[100:103], v[164:167], v[188:191], v[100:103]
	v_mfma_f32_16x16x32_bf16 v[96:99], v[172:175], v[188:191], v[96:99]
	v_mfma_f32_16x16x32_bf16 v[84:87], v[164:167], v[196:199], v[84:87]
	v_mfma_f32_16x16x32_bf16 v[80:83], v[172:175], v[196:199], v[80:83]
	v_mfma_f32_16x16x32_bf16 v[68:71], v[164:167], v[212:215], v[68:71]
	v_mfma_f32_16x16x32_bf16 v[64:67], v[172:175], v[212:215], v[64:67]
	v_mfma_f32_16x16x32_bf16 v[116:119], v[168:171], v[184:187], v[116:119]
	v_mfma_f32_16x16x32_bf16 v[112:115], v[176:179], v[184:187], v[112:115]
	v_mfma_f32_16x16x32_bf16 v[100:103], v[168:171], v[192:195], v[100:103]
	v_mfma_f32_16x16x32_bf16 v[96:99], v[176:179], v[192:195], v[96:99]
	v_mfma_f32_16x16x32_bf16 v[84:87], v[168:171], v[200:203], v[84:87]
	v_mfma_f32_16x16x32_bf16 v[80:83], v[176:179], v[200:203], v[80:83]
	v_mfma_f32_16x16x32_bf16 v[68:71], v[168:171], v[220:223], v[68:71]
	v_mfma_f32_16x16x32_bf16 v[64:67], v[176:179], v[220:223], v[64:67]
	s_barrier
	s_add_i32 s54, s54, s37
	v_lshl_add_u64 v[146:147], s[22:23], 0, v[148:149]
	s_mov_b32 m0, s54
	ds_read_b128 v[180:183], v159 offset:16384
	ds_read_b128 v[184:187], v159 offset:17408
	ds_read_b128 v[188:191], v159 offset:18432
	ds_read_b128 v[192:195], v159 offset:19456
	ds_read_b128 v[196:199], v159 offset:20480
	ds_read_b128 v[200:203], v159 offset:21504
	ds_read_b128 v[212:215], v159 offset:22528
	ds_read_b128 v[220:223], v159 offset:23552
	global_load_lds_dwordx4 v[146:147], off
	s_add_i32 m0, s54, 0x2000
	s_add_u32 s54, s22, 0x20000
	v_lshl_add_u64 v[150:151], s[22:23], 0, v[128:129]
	s_addc_u32 s55, s23, 0
	s_add_i32 s56, s56, s37
	global_load_lds_dwordx4 v[150:151], off
	v_lshl_add_u64 v[152:153], s[54:55], 0, v[148:149]
	s_mov_b32 m0, s56
	v_lshl_add_u64 v[204:205], s[24:25], 0, v[130:131]
	global_load_lds_dwordx4 v[152:153], off
	v_lshl_add_u64 v[152:153], s[54:55], 0, v[128:129]
	s_add_i32 m0, s56, 0x2000
	s_nop 0
	global_load_lds_dwordx4 v[152:153], off
	v_lshl_add_u64 v[152:153], s[24:25], 0, v[132:133]
	s_mov_b32 m0, s38
	s_nop 0
	global_load_lds_dwordx4 v[152:153], off
	s_mov_b32 m0, s39
	s_nop 0
	global_load_lds_dwordx4 v[204:205], off
	s_waitcnt vmcnt(8)
	s_waitcnt lgkmcnt(0)
	s_barrier
	s_waitcnt lgkmcnt(0)
	v_mfma_f32_16x16x32_bf16 v[60:63], v[138:141], v[180:183], v[60:63]
	v_mfma_f32_16x16x32_bf16 v[56:59], v[154:157], v[180:183], v[56:59]
	v_mfma_f32_16x16x32_bf16 v[44:47], v[138:141], v[188:191], v[44:47]
	v_mfma_f32_16x16x32_bf16 v[40:43], v[154:157], v[188:191], v[40:43]
	v_mfma_f32_16x16x32_bf16 v[28:31], v[138:141], v[196:199], v[28:31]
	v_mfma_f32_16x16x32_bf16 v[24:27], v[154:157], v[196:199], v[24:27]
	v_mfma_f32_16x16x32_bf16 v[12:15], v[138:141], v[212:215], v[12:15]
	v_mfma_f32_16x16x32_bf16 v[8:11], v[154:157], v[212:215], v[8:11]
	v_mfma_f32_16x16x32_bf16 v[60:63], v[142:145], v[184:187], v[60:63]
	v_mfma_f32_16x16x32_bf16 v[56:59], v[160:163], v[184:187], v[56:59]
	v_mfma_f32_16x16x32_bf16 v[44:47], v[142:145], v[192:195], v[44:47]
	v_mfma_f32_16x16x32_bf16 v[40:43], v[160:163], v[192:195], v[40:43]
	v_mfma_f32_16x16x32_bf16 v[28:31], v[142:145], v[200:203], v[28:31]
	v_mfma_f32_16x16x32_bf16 v[24:27], v[160:163], v[200:203], v[24:27]
	v_mfma_f32_16x16x32_bf16 v[12:15], v[142:145], v[220:223], v[12:15]
	v_mfma_f32_16x16x32_bf16 v[8:11], v[160:163], v[220:223], v[8:11]
	v_mfma_f32_16x16x32_bf16 v[52:55], v[164:167], v[180:183], v[52:55]
	v_mfma_f32_16x16x32_bf16 v[48:51], v[172:175], v[180:183], v[48:51]
	v_mfma_f32_16x16x32_bf16 v[36:39], v[164:167], v[188:191], v[36:39]
	v_mfma_f32_16x16x32_bf16 v[32:35], v[172:175], v[188:191], v[32:35]
	v_mfma_f32_16x16x32_bf16 v[20:23], v[164:167], v[196:199], v[20:23]
	v_mfma_f32_16x16x32_bf16 v[16:19], v[172:175], v[196:199], v[16:19]
	v_mfma_f32_16x16x32_bf16 v[4:7], v[164:167], v[212:215], v[4:7]
	v_mfma_f32_16x16x32_bf16 v[0:3], v[172:175], v[212:215], v[0:3]
	v_mfma_f32_16x16x32_bf16 v[52:55], v[168:171], v[184:187], v[52:55]
	v_mfma_f32_16x16x32_bf16 v[48:51], v[176:179], v[184:187], v[48:51]
	v_mfma_f32_16x16x32_bf16 v[36:39], v[168:171], v[192:195], v[36:39]
	v_mfma_f32_16x16x32_bf16 v[32:35], v[176:179], v[192:195], v[32:35]
	v_mfma_f32_16x16x32_bf16 v[20:23], v[168:171], v[200:203], v[20:23]
	v_mfma_f32_16x16x32_bf16 v[16:19], v[176:179], v[200:203], v[16:19]
	v_mfma_f32_16x16x32_bf16 v[4:7], v[168:171], v[220:223], v[4:7]
	v_mfma_f32_16x16x32_bf16 v[0:3], v[176:179], v[220:223], v[0:3]
	s_barrier
	s_add_i32 s54, 0, 0x18000
	s_add_i32 s55, 0, 0x1c000
	v_add_u32_e32 v160, s54, v158
	v_add_u32_e32 v176, s55, v158
	ds_read_b128 v[138:141], v160
	ds_read_b128 v[142:145], v160 offset:1024
	ds_read_b128 v[154:157], v160 offset:2048
	ds_read_b128 v[160:163], v160 offset:3072
	ds_read_b128 v[164:167], v176
	ds_read_b128 v[168:171], v176 offset:1024
	ds_read_b128 v[172:175], v176 offset:2048
	ds_read_b128 v[176:179], v176 offset:3072
	s_add_u32 s24, s24, 0x20000
	s_addc_u32 s25, s25, 0
	s_mov_b32 m0, s40
	v_lshl_add_u64 v[208:209], s[24:25], 0, v[132:133]
	ds_read_b128 v[180:183], v159 offset:32768
	ds_read_b128 v[184:187], v159 offset:33792
	ds_read_b128 v[188:191], v159 offset:34816
	ds_read_b128 v[192:195], v159 offset:35840
	ds_read_b128 v[196:199], v159 offset:36864
	ds_read_b128 v[200:203], v159 offset:37888
	ds_read_b128 v[212:215], v159 offset:38912
	ds_read_b128 v[220:223], v159 offset:39936
	global_load_lds_dwordx4 v[208:209], off
	v_lshl_add_u64 v[208:209], s[24:25], 0, v[130:131]
	s_mov_b32 m0, s41
	s_nop 0
	global_load_lds_dwordx4 v[208:209], off
	s_waitcnt vmcnt(8)
	s_waitcnt lgkmcnt(0)
	s_barrier
	s_waitcnt lgkmcnt(0)
	v_mfma_f32_16x16x32_bf16 v[124:127], v[138:141], v[180:183], v[124:127]
	v_mfma_f32_16x16x32_bf16 v[120:123], v[154:157], v[180:183], v[120:123]
	v_mfma_f32_16x16x32_bf16 v[108:111], v[138:141], v[188:191], v[108:111]
	v_mfma_f32_16x16x32_bf16 v[104:107], v[154:157], v[188:191], v[104:107]
	v_mfma_f32_16x16x32_bf16 v[92:95], v[138:141], v[196:199], v[92:95]
	v_mfma_f32_16x16x32_bf16 v[88:91], v[154:157], v[196:199], v[88:91]
	v_mfma_f32_16x16x32_bf16 v[76:79], v[138:141], v[212:215], v[76:79]
	v_mfma_f32_16x16x32_bf16 v[72:75], v[154:157], v[212:215], v[72:75]
	v_mfma_f32_16x16x32_bf16 v[124:127], v[142:145], v[184:187], v[124:127]
	v_mfma_f32_16x16x32_bf16 v[120:123], v[160:163], v[184:187], v[120:123]
	v_mfma_f32_16x16x32_bf16 v[108:111], v[142:145], v[192:195], v[108:111]
	v_mfma_f32_16x16x32_bf16 v[104:107], v[160:163], v[192:195], v[104:107]
	v_mfma_f32_16x16x32_bf16 v[92:95], v[142:145], v[200:203], v[92:95]
	v_mfma_f32_16x16x32_bf16 v[88:91], v[160:163], v[200:203], v[88:91]
	v_mfma_f32_16x16x32_bf16 v[76:79], v[142:145], v[220:223], v[76:79]
	v_mfma_f32_16x16x32_bf16 v[72:75], v[160:163], v[220:223], v[72:75]
	v_mfma_f32_16x16x32_bf16 v[116:119], v[164:167], v[180:183], v[116:119]
	v_mfma_f32_16x16x32_bf16 v[112:115], v[172:175], v[180:183], v[112:115]
	v_mfma_f32_16x16x32_bf16 v[100:103], v[164:167], v[188:191], v[100:103]
	v_mfma_f32_16x16x32_bf16 v[96:99], v[172:175], v[188:191], v[96:99]
	v_mfma_f32_16x16x32_bf16 v[84:87], v[164:167], v[196:199], v[84:87]
	v_mfma_f32_16x16x32_bf16 v[80:83], v[172:175], v[196:199], v[80:83]
	v_mfma_f32_16x16x32_bf16 v[68:71], v[164:167], v[212:215], v[68:71]
	v_mfma_f32_16x16x32_bf16 v[64:67], v[172:175], v[212:215], v[64:67]
	v_mfma_f32_16x16x32_bf16 v[116:119], v[168:171], v[184:187], v[116:119]
	v_mfma_f32_16x16x32_bf16 v[112:115], v[176:179], v[184:187], v[112:115]
	v_mfma_f32_16x16x32_bf16 v[100:103], v[168:171], v[192:195], v[100:103]
	v_mfma_f32_16x16x32_bf16 v[96:99], v[176:179], v[192:195], v[96:99]
	v_mfma_f32_16x16x32_bf16 v[84:87], v[168:171], v[200:203], v[84:87]
	v_mfma_f32_16x16x32_bf16 v[80:83], v[176:179], v[200:203], v[80:83]
	v_mfma_f32_16x16x32_bf16 v[68:71], v[168:171], v[220:223], v[68:71]
	v_mfma_f32_16x16x32_bf16 v[64:67], v[176:179], v[220:223], v[64:67]
	s_barrier
	s_add_i32 s24, s54, s37
	v_lshl_add_u64 v[146:147], v[146:147], 0, s[28:29]
	s_mov_b32 m0, s24
	ds_read_b128 v[180:183], v159 offset:49152
	ds_read_b128 v[184:187], v159 offset:50176
	ds_read_b128 v[188:191], v159 offset:51200
	ds_read_b128 v[192:195], v159 offset:52224
	ds_read_b128 v[196:199], v159 offset:53248
	ds_read_b128 v[200:203], v159 offset:54272
	ds_read_b128 v[212:215], v159 offset:55296
	ds_read_b128 v[220:223], v159 offset:56320
	global_load_lds_dwordx4 v[146:147], off
	s_add_i32 m0, s24, 0x2000
	s_add_u32 s22, s22, 0x20080
	v_lshl_add_u64 v[146:147], v[150:151], 0, s[28:29]
	s_addc_u32 s23, s23, 0
	s_add_i32 s24, s55, s37
	global_load_lds_dwordx4 v[146:147], off
	v_lshl_add_u64 v[146:147], s[22:23], 0, v[148:149]
	s_mov_b32 m0, s24
	s_nop 0
	global_load_lds_dwordx4 v[146:147], off
	v_lshl_add_u64 v[146:147], s[22:23], 0, v[128:129]
	s_add_i32 m0, s24, 0x2000
	s_nop 0
	global_load_lds_dwordx4 v[146:147], off
	v_lshl_add_u64 v[146:147], v[152:153], 0, s[28:29]
	s_mov_b32 m0, s45
	s_nop 0
	global_load_lds_dwordx4 v[146:147], off
	v_lshl_add_u64 v[146:147], v[204:205], 0, s[28:29]
	s_mov_b32 m0, s46
	s_nop 0
	global_load_lds_dwordx4 v[146:147], off
	s_waitcnt vmcnt(8)
	s_waitcnt lgkmcnt(0)
	s_barrier
	s_waitcnt lgkmcnt(0)
	v_mfma_f32_16x16x32_bf16 v[60:63], v[138:141], v[180:183], v[60:63]
	v_mfma_f32_16x16x32_bf16 v[56:59], v[154:157], v[180:183], v[56:59]
	v_mfma_f32_16x16x32_bf16 v[44:47], v[138:141], v[188:191], v[44:47]
	v_mfma_f32_16x16x32_bf16 v[40:43], v[154:157], v[188:191], v[40:43]
	v_mfma_f32_16x16x32_bf16 v[28:31], v[138:141], v[196:199], v[28:31]
	v_mfma_f32_16x16x32_bf16 v[24:27], v[154:157], v[196:199], v[24:27]
	v_mfma_f32_16x16x32_bf16 v[12:15], v[138:141], v[212:215], v[12:15]
	v_mfma_f32_16x16x32_bf16 v[8:11], v[154:157], v[212:215], v[8:11]
	v_mfma_f32_16x16x32_bf16 v[60:63], v[142:145], v[184:187], v[60:63]
	v_mfma_f32_16x16x32_bf16 v[56:59], v[160:163], v[184:187], v[56:59]
	v_mfma_f32_16x16x32_bf16 v[44:47], v[142:145], v[192:195], v[44:47]
	v_mfma_f32_16x16x32_bf16 v[40:43], v[160:163], v[192:195], v[40:43]
	v_mfma_f32_16x16x32_bf16 v[28:31], v[142:145], v[200:203], v[28:31]
	v_mfma_f32_16x16x32_bf16 v[24:27], v[160:163], v[200:203], v[24:27]
	v_mfma_f32_16x16x32_bf16 v[12:15], v[142:145], v[220:223], v[12:15]
	v_mfma_f32_16x16x32_bf16 v[8:11], v[160:163], v[220:223], v[8:11]
	v_mfma_f32_16x16x32_bf16 v[52:55], v[164:167], v[180:183], v[52:55]
	v_mfma_f32_16x16x32_bf16 v[48:51], v[172:175], v[180:183], v[48:51]
	v_mfma_f32_16x16x32_bf16 v[36:39], v[164:167], v[188:191], v[36:39]
	v_mfma_f32_16x16x32_bf16 v[32:35], v[172:175], v[188:191], v[32:35]
	v_mfma_f32_16x16x32_bf16 v[20:23], v[164:167], v[196:199], v[20:23]
	v_mfma_f32_16x16x32_bf16 v[16:19], v[172:175], v[196:199], v[16:19]
	v_mfma_f32_16x16x32_bf16 v[4:7], v[164:167], v[212:215], v[4:7]
	v_mfma_f32_16x16x32_bf16 v[0:3], v[172:175], v[212:215], v[0:3]
	v_mfma_f32_16x16x32_bf16 v[52:55], v[168:171], v[184:187], v[52:55]
	v_mfma_f32_16x16x32_bf16 v[48:51], v[176:179], v[184:187], v[48:51]
	v_mfma_f32_16x16x32_bf16 v[36:39], v[168:171], v[192:195], v[36:39]
	v_mfma_f32_16x16x32_bf16 v[32:35], v[176:179], v[192:195], v[32:35]
	v_mfma_f32_16x16x32_bf16 v[20:23], v[168:171], v[200:203], v[20:23]
	v_mfma_f32_16x16x32_bf16 v[16:19], v[176:179], v[200:203], v[16:19]
	v_mfma_f32_16x16x32_bf16 v[4:7], v[168:171], v[220:223], v[4:7]
	v_mfma_f32_16x16x32_bf16 v[0:3], v[176:179], v[220:223], v[0:3]
	s_barrier
	s_add_i32 s53, s53, 2
	s_add_u32 s8, s8, 0x100
	s_addc_u32 s9, s9, 0
	s_add_u32 s51, s51, 0x100
	s_addc_u32 s52, s52, 0
	s_cmp_gt_u32 s53, 5
	s_cbranch_scc0 .LBB0_1335
	s_and_b64 vcc, exec, s[12:13]
	s_cbranch_vccz .LBB0_1338
	s_barrier

.LBB0_1437:
	s_ashr_i32 s13, s12, 31
	s_lshl_b64 s[14:15], s[12:13], 19
	s_add_u32 s14, s24, s14
	s_addc_u32 s15, s25, s15
	s_and_b64 s[16:17], s[4:5], exec
	s_cselect_b32 s13, s15, s19
	s_cselect_b32 s44, s14, s18
	s_ashr_i32 s11, s10, 31
	s_lshl_b64 s[16:17], s[10:11], 19
	s_add_u32 s16, s26, s16
	s_addc_u32 s17, s27, s17
	s_and_b64 s[22:23], s[4:5], exec
	s_cselect_b32 s11, s17, s21
	s_cselect_b32 s45, s16, s20
	s_add_u32 s18, s18, 0x40080
	s_addc_u32 s19, s19, 0
	s_add_u32 s46, s20, 0x100
	s_mov_b32 s53, s49
	s_addc_u32 s47, s21, 0
	s_mov_b32 s48, -2
	.p2alignl 6, 3212836864
.LBB0_1438:
	s_add_u32 s20, s18, 0xfffc0080
	s_addc_u32 s21, s19, -1
	s_add_i32 s49, 0, 0x10000
	s_cmp_eq_u32 s48, 12
	s_cselect_b32 s23, s13, s21
	s_cselect_b32 s22, s44, s20
	v_add_u32_e32 v142, s49, v144
	s_cselect_b32 s21, s11, s47
	s_cselect_b32 s20, s45, s46
	s_add_i32 s52, 0, 0x14000
	ds_read_b128 v[138:141], v142
	ds_read_b128 v[154:157], v142 offset:1024
	ds_read_b128 v[158:161], v142 offset:2048
	ds_read_b128 v[162:165], v142 offset:3072
	v_add_u32_e32 v142, s52, v144
	ds_read_b128 v[166:169], v142
	ds_read_b128 v[170:173], v142 offset:1024
	ds_read_b128 v[174:177], v142 offset:2048
	ds_read_b128 v[178:181], v142 offset:3072
	v_lshl_add_u64 v[142:143], s[18:19], 0, v[134:135]
	s_add_i32 m0, s31, 0xc000
	ds_read_b128 v[182:185], v145
	ds_read_b128 v[186:189], v145 offset:1024
	ds_read_b128 v[190:193], v145 offset:2048
	ds_read_b128 v[194:197], v145 offset:3072
	ds_read_b128 v[198:201], v145 offset:4096
	ds_read_b128 v[202:205], v145 offset:5120
	ds_read_b128 v[212:215], v145 offset:6144
	ds_read_b128 v[220:223], v145 offset:7168
	global_load_lds_dwordx4 v[142:143], off
	v_lshl_add_u64 v[142:143], s[18:19], 0, v[136:137]
	s_add_i32 m0, s31, 0xe000
	s_nop 0
	global_load_lds_dwordx4 v[142:143], off
	s_cmp_lg_u32 s48, -2
	s_cbranch_scc1 .Lz_skip_5
	v_mov_b64_e32 v[0:1], 0
	v_mov_b64_e32 v[2:3], 0
	v_mov_b64_e32 v[4:5], 0
	v_mov_b64_e32 v[6:7], 0
	v_mov_b64_e32 v[16:17], 0
	v_mov_b64_e32 v[18:19], 0
	v_mov_b64_e32 v[20:21], 0
	v_mov_b64_e32 v[22:23], 0
	v_mov_b64_e32 v[32:33], 0
	v_mov_b64_e32 v[34:35], 0
	v_mov_b64_e32 v[36:37], 0
	v_mov_b64_e32 v[38:39], 0
	v_mov_b64_e32 v[48:49], 0
	v_mov_b64_e32 v[50:51], 0
	v_mov_b64_e32 v[52:53], 0
	v_mov_b64_e32 v[54:55], 0
	v_mov_b64_e32 v[8:9], 0
	v_mov_b64_e32 v[10:11], 0
	v_mov_b64_e32 v[12:13], 0
	v_mov_b64_e32 v[14:15], 0
	v_mov_b64_e32 v[24:25], 0
	v_mov_b64_e32 v[26:27], 0
	v_mov_b64_e32 v[28:29], 0
	v_mov_b64_e32 v[30:31], 0
	v_mov_b64_e32 v[40:41], 0
	v_mov_b64_e32 v[42:43], 0
	v_mov_b64_e32 v[44:45], 0
	v_mov_b64_e32 v[46:47], 0
	v_mov_b64_e32 v[56:57], 0
	v_mov_b64_e32 v[58:59], 0
	v_mov_b64_e32 v[60:61], 0
	v_mov_b64_e32 v[62:63], 0
	v_mov_b64_e32 v[64:65], 0
	v_mov_b64_e32 v[66:67], 0
	v_mov_b64_e32 v[68:69], 0
	v_mov_b64_e32 v[70:71], 0
	v_mov_b64_e32 v[80:81], 0
	v_mov_b64_e32 v[82:83], 0
	v_mov_b64_e32 v[84:85], 0
	v_mov_b64_e32 v[86:87], 0
	v_mov_b64_e32 v[96:97], 0
	v_mov_b64_e32 v[98:99], 0
	v_mov_b64_e32 v[100:101], 0
	v_mov_b64_e32 v[102:103], 0
	v_mov_b64_e32 v[112:113], 0
	v_mov_b64_e32 v[114:115], 0
	v_mov_b64_e32 v[116:117], 0
	v_mov_b64_e32 v[118:119], 0
	v_mov_b64_e32 v[72:73], 0
	v_mov_b64_e32 v[74:75], 0
	v_mov_b64_e32 v[76:77], 0
	v_mov_b64_e32 v[78:79], 0
	v_mov_b64_e32 v[88:89], 0
	v_mov_b64_e32 v[90:91], 0
	v_mov_b64_e32 v[92:93], 0
	v_mov_b64_e32 v[94:95], 0
	v_mov_b64_e32 v[104:105], 0
	v_mov_b64_e32 v[106:107], 0
	v_mov_b64_e32 v[108:109], 0
	v_mov_b64_e32 v[110:111], 0
	v_mov_b64_e32 v[120:121], 0
	v_mov_b64_e32 v[122:123], 0
	v_mov_b64_e32 v[124:125], 0
	v_mov_b64_e32 v[126:127], 0
.Lz_skip_5:
	s_waitcnt vmcnt(8)
	s_waitcnt lgkmcnt(0)
	s_barrier
	s_waitcnt lgkmcnt(0)
	v_mfma_f32_16x16x32_bf16 v[124:127], v[138:141], v[182:185], v[124:127]
	v_mfma_f32_16x16x32_bf16 v[120:123], v[158:161], v[182:185], v[120:123]
	v_mfma_f32_16x16x32_bf16 v[108:111], v[138:141], v[190:193], v[108:111]
	v_mfma_f32_16x16x32_bf16 v[104:107], v[158:161], v[190:193], v[104:107]
	v_mfma_f32_16x16x32_bf16 v[92:95], v[138:141], v[198:201], v[92:95]
	v_mfma_f32_16x16x32_bf16 v[88:91], v[158:161], v[198:201], v[88:91]
	v_mfma_f32_16x16x32_bf16 v[76:79], v[138:141], v[212:215], v[76:79]
	v_mfma_f32_16x16x32_bf16 v[72:75], v[158:161], v[212:215], v[72:75]
	v_mfma_f32_16x16x32_bf16 v[124:127], v[154:157], v[186:189], v[124:127]
	v_mfma_f32_16x16x32_bf16 v[120:123], v[162:165], v[186:189], v[120:123]
	v_mfma_f32_16x16x32_bf16 v[108:111], v[154:157], v[194:197], v[108:111]
	v_mfma_f32_16x16x32_bf16 v[104:107], v[162:165], v[194:197], v[104:107]
	v_mfma_f32_16x16x32_bf16 v[92:95], v[154:157], v[202:205], v[92:95]
	v_mfma_f32_16x16x32_bf16 v[88:91], v[162:165], v[202:205], v[88:91]
	v_mfma_f32_16x16x32_bf16 v[76:79], v[154:157], v[220:223], v[76:79]
	v_mfma_f32_16x16x32_bf16 v[72:75], v[162:165], v[220:223], v[72:75]
	v_mfma_f32_16x16x32_bf16 v[116:119], v[166:169], v[182:185], v[116:119]
	v_mfma_f32_16x16x32_bf16 v[112:115], v[174:177], v[182:185], v[112:115]
	v_mfma_f32_16x16x32_bf16 v[100:103], v[166:169], v[190:193], v[100:103]
	v_mfma_f32_16x16x32_bf16 v[96:99], v[174:177], v[190:193], v[96:99]
	v_mfma_f32_16x16x32_bf16 v[84:87], v[166:169], v[198:201], v[84:87]
	v_mfma_f32_16x16x32_bf16 v[80:83], v[174:177], v[198:201], v[80:83]
	v_mfma_f32_16x16x32_bf16 v[68:71], v[166:169], v[212:215], v[68:71]
	v_mfma_f32_16x16x32_bf16 v[64:67], v[174:177], v[212:215], v[64:67]
	v_mfma_f32_16x16x32_bf16 v[116:119], v[170:173], v[186:189], v[116:119]
	v_mfma_f32_16x16x32_bf16 v[112:115], v[178:181], v[186:189], v[112:115]
	v_mfma_f32_16x16x32_bf16 v[100:103], v[170:173], v[194:197], v[100:103]
	v_mfma_f32_16x16x32_bf16 v[96:99], v[178:181], v[194:197], v[96:99]
	v_mfma_f32_16x16x32_bf16 v[84:87], v[170:173], v[202:205], v[84:87]
	v_mfma_f32_16x16x32_bf16 v[80:83], v[178:181], v[202:205], v[80:83]
	v_mfma_f32_16x16x32_bf16 v[68:71], v[170:173], v[220:223], v[68:71]
	v_mfma_f32_16x16x32_bf16 v[64:67], v[178:181], v[220:223], v[64:67]
	s_barrier
	s_add_i32 s49, s49, s30
	v_lshl_add_u64 v[142:143], s[20:21], 0, v[148:149]
	s_mov_b32 m0, s49
	ds_read_b128 v[182:185], v145 offset:16384
	ds_read_b128 v[186:189], v145 offset:17408
	ds_read_b128 v[190:193], v145 offset:18432
	ds_read_b128 v[194:197], v145 offset:19456
	ds_read_b128 v[198:201], v145 offset:20480
	ds_read_b128 v[202:205], v145 offset:21504
	ds_read_b128 v[212:215], v145 offset:22528
	ds_read_b128 v[220:223], v145 offset:23552
	global_load_lds_dwordx4 v[142:143], off
	s_add_i32 m0, s49, 0x2000
	s_add_u32 s50, s20, 0x40000
	v_lshl_add_u64 v[146:147], s[20:21], 0, v[128:129]
	s_addc_u32 s51, s21, 0
	s_add_i32 s49, s52, s30
	global_load_lds_dwordx4 v[146:147], off
	v_lshl_add_u64 v[150:151], s[50:51], 0, v[148:149]
	s_mov_b32 m0, s49
	v_lshl_add_u64 v[152:153], s[22:23], 0, v[130:131]
	global_load_lds_dwordx4 v[150:151], off
	v_lshl_add_u64 v[150:151], s[50:51], 0, v[128:129]
	s_add_i32 m0, s49, 0x2000
	s_nop 0
	global_load_lds_dwordx4 v[150:151], off
	v_lshl_add_u64 v[150:151], s[22:23], 0, v[132:133]
	s_mov_b32 m0, s31
	s_nop 0
	global_load_lds_dwordx4 v[150:151], off
	s_mov_b32 m0, s33
	s_nop 0
	global_load_lds_dwordx4 v[152:153], off
	s_waitcnt vmcnt(8)
	s_waitcnt lgkmcnt(0)
	s_barrier
	s_waitcnt lgkmcnt(0)
	v_mfma_f32_16x16x32_bf16 v[60:63], v[138:141], v[182:185], v[60:63]
	v_mfma_f32_16x16x32_bf16 v[56:59], v[158:161], v[182:185], v[56:59]
	v_mfma_f32_16x16x32_bf16 v[44:47], v[138:141], v[190:193], v[44:47]
	v_mfma_f32_16x16x32_bf16 v[40:43], v[158:161], v[190:193], v[40:43]
	v_mfma_f32_16x16x32_bf16 v[28:31], v[138:141], v[198:201], v[28:31]
	v_mfma_f32_16x16x32_bf16 v[24:27], v[158:161], v[198:201], v[24:27]
	v_mfma_f32_16x16x32_bf16 v[12:15], v[138:141], v[212:215], v[12:15]
	v_mfma_f32_16x16x32_bf16 v[8:11], v[158:161], v[212:215], v[8:11]
	v_mfma_f32_16x16x32_bf16 v[60:63], v[154:157], v[186:189], v[60:63]
	v_mfma_f32_16x16x32_bf16 v[56:59], v[162:165], v[186:189], v[56:59]
	v_mfma_f32_16x16x32_bf16 v[44:47], v[154:157], v[194:197], v[44:47]
	v_mfma_f32_16x16x32_bf16 v[40:43], v[162:165], v[194:197], v[40:43]
	v_mfma_f32_16x16x32_bf16 v[28:31], v[154:157], v[202:205], v[28:31]
	v_mfma_f32_16x16x32_bf16 v[24:27], v[162:165], v[202:205], v[24:27]
	v_mfma_f32_16x16x32_bf16 v[12:15], v[154:157], v[220:223], v[12:15]
	v_mfma_f32_16x16x32_bf16 v[8:11], v[162:165], v[220:223], v[8:11]
	v_mfma_f32_16x16x32_bf16 v[52:55], v[166:169], v[182:185], v[52:55]
	v_mfma_f32_16x16x32_bf16 v[48:51], v[174:177], v[182:185], v[48:51]
	v_mfma_f32_16x16x32_bf16 v[36:39], v[166:169], v[190:193], v[36:39]
	v_mfma_f32_16x16x32_bf16 v[32:35], v[174:177], v[190:193], v[32:35]
	v_mfma_f32_16x16x32_bf16 v[20:23], v[166:169], v[198:201], v[20:23]
	v_mfma_f32_16x16x32_bf16 v[16:19], v[174:177], v[198:201], v[16:19]
	v_mfma_f32_16x16x32_bf16 v[4:7], v[166:169], v[212:215], v[4:7]
	v_mfma_f32_16x16x32_bf16 v[0:3], v[174:177], v[212:215], v[0:3]
	v_mfma_f32_16x16x32_bf16 v[52:55], v[170:173], v[186:189], v[52:55]
	v_mfma_f32_16x16x32_bf16 v[48:51], v[178:181], v[186:189], v[48:51]
	v_mfma_f32_16x16x32_bf16 v[36:39], v[170:173], v[194:197], v[36:39]
	v_mfma_f32_16x16x32_bf16 v[32:35], v[178:181], v[194:197], v[32:35]
	v_mfma_f32_16x16x32_bf16 v[20:23], v[170:173], v[202:205], v[20:23]
	v_mfma_f32_16x16x32_bf16 v[16:19], v[178:181], v[202:205], v[16:19]
	v_mfma_f32_16x16x32_bf16 v[4:7], v[170:173], v[220:223], v[4:7]
	v_mfma_f32_16x16x32_bf16 v[0:3], v[178:181], v[220:223], v[0:3]
	s_barrier
	s_add_i32 s49, 0, 0x18000
	s_add_i32 s50, 0, 0x1c000
	v_add_u32_e32 v162, s49, v144
	v_add_u32_e32 v178, s50, v144
	ds_read_b128 v[138:141], v162
	ds_read_b128 v[154:157], v162 offset:1024
	ds_read_b128 v[158:161], v162 offset:2048
	ds_read_b128 v[162:165], v162 offset:3072
	ds_read_b128 v[166:169], v178
	ds_read_b128 v[170:173], v178 offset:1024
	ds_read_b128 v[174:177], v178 offset:2048
	ds_read_b128 v[178:181], v178 offset:3072
	s_add_u32 s22, s22, 0x40000
	s_addc_u32 s23, s23, 0
	s_mov_b32 m0, s34
	v_lshl_add_u64 v[208:209], s[22:23], 0, v[132:133]
	ds_read_b128 v[182:185], v145 offset:32768
	ds_read_b128 v[186:189], v145 offset:33792
	ds_read_b128 v[190:193], v145 offset:34816
	ds_read_b128 v[194:197], v145 offset:35840
	ds_read_b128 v[198:201], v145 offset:36864
	ds_read_b128 v[202:205], v145 offset:37888
	ds_read_b128 v[212:215], v145 offset:38912
	ds_read_b128 v[220:223], v145 offset:39936
	global_load_lds_dwordx4 v[208:209], off
	v_lshl_add_u64 v[208:209], s[22:23], 0, v[130:131]
	s_mov_b32 m0, s35
	s_nop 0
	global_load_lds_dwordx4 v[208:209], off
	s_waitcnt vmcnt(8)
	s_waitcnt lgkmcnt(0)
	s_barrier
	s_waitcnt lgkmcnt(0)
	v_mfma_f32_16x16x32_bf16 v[124:127], v[138:141], v[182:185], v[124:127]
	v_mfma_f32_16x16x32_bf16 v[120:123], v[158:161], v[182:185], v[120:123]
	v_mfma_f32_16x16x32_bf16 v[108:111], v[138:141], v[190:193], v[108:111]
	v_mfma_f32_16x16x32_bf16 v[104:107], v[158:161], v[190:193], v[104:107]
	v_mfma_f32_16x16x32_bf16 v[92:95], v[138:141], v[198:201], v[92:95]
	v_mfma_f32_16x16x32_bf16 v[88:91], v[158:161], v[198:201], v[88:91]
	v_mfma_f32_16x16x32_bf16 v[76:79], v[138:141], v[212:215], v[76:79]
	v_mfma_f32_16x16x32_bf16 v[72:75], v[158:161], v[212:215], v[72:75]
	v_mfma_f32_16x16x32_bf16 v[124:127], v[154:157], v[186:189], v[124:127]
	v_mfma_f32_16x16x32_bf16 v[120:123], v[162:165], v[186:189], v[120:123]
	v_mfma_f32_16x16x32_bf16 v[108:111], v[154:157], v[194:197], v[108:111]
	v_mfma_f32_16x16x32_bf16 v[104:107], v[162:165], v[194:197], v[104:107]
	v_mfma_f32_16x16x32_bf16 v[92:95], v[154:157], v[202:205], v[92:95]
	v_mfma_f32_16x16x32_bf16 v[88:91], v[162:165], v[202:205], v[88:91]
	v_mfma_f32_16x16x32_bf16 v[76:79], v[154:157], v[220:223], v[76:79]
	v_mfma_f32_16x16x32_bf16 v[72:75], v[162:165], v[220:223], v[72:75]
	v_mfma_f32_16x16x32_bf16 v[116:119], v[166:169], v[182:185], v[116:119]
	v_mfma_f32_16x16x32_bf16 v[112:115], v[174:177], v[182:185], v[112:115]
	v_mfma_f32_16x16x32_bf16 v[100:103], v[166:169], v[190:193], v[100:103]
	v_mfma_f32_16x16x32_bf16 v[96:99], v[174:177], v[190:193], v[96:99]
	v_mfma_f32_16x16x32_bf16 v[84:87], v[166:169], v[198:201], v[84:87]
	v_mfma_f32_16x16x32_bf16 v[80:83], v[174:177], v[198:201], v[80:83]
	v_mfma_f32_16x16x32_bf16 v[68:71], v[166:169], v[212:215], v[68:71]
	v_mfma_f32_16x16x32_bf16 v[64:67], v[174:177], v[212:215], v[64:67]
	v_mfma_f32_16x16x32_bf16 v[116:119], v[170:173], v[186:189], v[116:119]
	v_mfma_f32_16x16x32_bf16 v[112:115], v[178:181], v[186:189], v[112:115]
	v_mfma_f32_16x16x32_bf16 v[100:103], v[170:173], v[194:197], v[100:103]
	v_mfma_f32_16x16x32_bf16 v[96:99], v[178:181], v[194:197], v[96:99]
	v_mfma_f32_16x16x32_bf16 v[84:87], v[170:173], v[202:205], v[84:87]
	v_mfma_f32_16x16x32_bf16 v[80:83], v[178:181], v[202:205], v[80:83]
	v_mfma_f32_16x16x32_bf16 v[68:71], v[170:173], v[220:223], v[68:71]
	v_mfma_f32_16x16x32_bf16 v[64:67], v[178:181], v[220:223], v[64:67]
	s_barrier
	s_add_i32 s22, s49, s30
	v_lshl_add_u64 v[142:143], v[142:143], 0, s[28:29]
	s_mov_b32 m0, s22
	ds_read_b128 v[182:185], v145 offset:49152
	ds_read_b128 v[186:189], v145 offset:50176
	ds_read_b128 v[190:193], v145 offset:51200
	ds_read_b128 v[194:197], v145 offset:52224
	ds_read_b128 v[198:201], v145 offset:53248
	ds_read_b128 v[202:205], v145 offset:54272
	ds_read_b128 v[212:215], v145 offset:55296
	ds_read_b128 v[220:223], v145 offset:56320
	global_load_lds_dwordx4 v[142:143], off
	s_add_i32 m0, s22, 0x2000
	s_add_u32 s20, s20, 0x40080
	v_lshl_add_u64 v[142:143], v[146:147], 0, s[28:29]
	s_addc_u32 s21, s21, 0
	s_add_i32 s22, s50, s30
	global_load_lds_dwordx4 v[142:143], off
	v_lshl_add_u64 v[142:143], s[20:21], 0, v[148:149]
	s_mov_b32 m0, s22
	s_nop 0
	global_load_lds_dwordx4 v[142:143], off
	v_lshl_add_u64 v[142:143], s[20:21], 0, v[128:129]
	s_add_i32 m0, s22, 0x2000
	s_nop 0
	global_load_lds_dwordx4 v[142:143], off
	v_lshl_add_u64 v[142:143], v[150:151], 0, s[28:29]
	s_mov_b32 m0, s39
	s_nop 0
	global_load_lds_dwordx4 v[142:143], off
	v_lshl_add_u64 v[142:143], v[152:153], 0, s[28:29]
	s_mov_b32 m0, s40
	s_nop 0
	global_load_lds_dwordx4 v[142:143], off
	s_waitcnt vmcnt(8)
	s_waitcnt lgkmcnt(0)
	s_barrier
	s_waitcnt lgkmcnt(0)
	v_mfma_f32_16x16x32_bf16 v[60:63], v[138:141], v[182:185], v[60:63]
	v_mfma_f32_16x16x32_bf16 v[56:59], v[158:161], v[182:185], v[56:59]
	v_mfma_f32_16x16x32_bf16 v[44:47], v[138:141], v[190:193], v[44:47]
	v_mfma_f32_16x16x32_bf16 v[40:43], v[158:161], v[190:193], v[40:43]
	v_mfma_f32_16x16x32_bf16 v[28:31], v[138:141], v[198:201], v[28:31]
	v_mfma_f32_16x16x32_bf16 v[24:27], v[158:161], v[198:201], v[24:27]
	v_mfma_f32_16x16x32_bf16 v[12:15], v[138:141], v[212:215], v[12:15]
	v_mfma_f32_16x16x32_bf16 v[8:11], v[158:161], v[212:215], v[8:11]
	v_mfma_f32_16x16x32_bf16 v[60:63], v[154:157], v[186:189], v[60:63]
	v_mfma_f32_16x16x32_bf16 v[56:59], v[162:165], v[186:189], v[56:59]
	v_mfma_f32_16x16x32_bf16 v[44:47], v[154:157], v[194:197], v[44:47]
	v_mfma_f32_16x16x32_bf16 v[40:43], v[162:165], v[194:197], v[40:43]
	v_mfma_f32_16x16x32_bf16 v[28:31], v[154:157], v[202:205], v[28:31]
	v_mfma_f32_16x16x32_bf16 v[24:27], v[162:165], v[202:205], v[24:27]
	v_mfma_f32_16x16x32_bf16 v[12:15], v[154:157], v[220:223], v[12:15]
	v_mfma_f32_16x16x32_bf16 v[8:11], v[162:165], v[220:223], v[8:11]
	v_mfma_f32_16x16x32_bf16 v[52:55], v[166:169], v[182:185], v[52:55]
	v_mfma_f32_16x16x32_bf16 v[48:51], v[174:177], v[182:185], v[48:51]
	v_mfma_f32_16x16x32_bf16 v[36:39], v[166:169], v[190:193], v[36:39]
	v_mfma_f32_16x16x32_bf16 v[32:35], v[174:177], v[190:193], v[32:35]
	v_mfma_f32_16x16x32_bf16 v[20:23], v[166:169], v[198:201], v[20:23]
	v_mfma_f32_16x16x32_bf16 v[16:19], v[174:177], v[198:201], v[16:19]
	v_mfma_f32_16x16x32_bf16 v[4:7], v[166:169], v[212:215], v[4:7]
	v_mfma_f32_16x16x32_bf16 v[0:3], v[174:177], v[212:215], v[0:3]
	v_mfma_f32_16x16x32_bf16 v[52:55], v[170:173], v[186:189], v[52:55]
	v_mfma_f32_16x16x32_bf16 v[48:51], v[178:181], v[186:189], v[48:51]
	v_mfma_f32_16x16x32_bf16 v[36:39], v[170:173], v[194:197], v[36:39]
	v_mfma_f32_16x16x32_bf16 v[32:35], v[178:181], v[194:197], v[32:35]
	v_mfma_f32_16x16x32_bf16 v[20:23], v[170:173], v[202:205], v[20:23]
	v_mfma_f32_16x16x32_bf16 v[16:19], v[178:181], v[202:205], v[16:19]
	v_mfma_f32_16x16x32_bf16 v[4:7], v[170:173], v[220:223], v[4:7]
	v_mfma_f32_16x16x32_bf16 v[0:3], v[178:181], v[220:223], v[0:3]
	s_barrier
	s_add_i32 s48, s48, 2
	s_add_u32 s18, s18, 0x100
	s_addc_u32 s19, s19, 0
	s_add_u32 s46, s46, 0x100
	s_addc_u32 s47, s47, 0
	s_cmp_gt_u32 s48, 13
	s_cbranch_scc0 .LBB0_1438
	s_and_b64 vcc, exec, s[8:9]
	s_cbranch_vccz .LBB0_1441
	s_barrier
